# v8 + LN-epilogue x (f32 residual) stores sc0 sc1 nt
# baseline (speedup 1.0000x reference)
.LBB0_279:
	s_or_b64 exec, exec, s[24:25]
	s_waitcnt lgkmcnt(0)
	s_barrier
	ds_write_b128 v175, v[128:131]
	ds_write_b128 v175, v[132:135] offset:64
	v_add_u32_e32 v194, v172, v178
	s_waitcnt lgkmcnt(2)
	v_cmp_eq_u32_e32 vcc, 0, v173
	ds_read_b128 v[130:133], v176
	ds_read_b128 v[170:173], v176 offset:1152
	ds_read2_b64 v[186:189], v181 offset1:8
	ds_write_b128 v175, v[136:139]
	ds_write_b128 v175, v[144:147] offset:64
	ds_read_b128 v[134:137], v176
	ds_read_b128 v[144:147], v176 offset:1152
	s_add_u32 s2, s20, s50
	v_ashrrev_i32_e32 v195, 31, v194
	s_addc_u32 s3, s21, s51
	v_lshl_add_u64 v[128:129], v[194:195], 1, s[22:23]
	s_mov_b64 s[14:15], 0x1ac00000
	s_waitcnt vmcnt(2)
	v_pk_add_f32 v[162:163], v[162:163], 1.0 op_sel_hi:[1,0]
	v_pk_add_f32 v[160:161], v[160:161], 1.0 op_sel_hi:[1,0]
	v_pk_add_f32 v[158:159], v[158:159], 1.0 op_sel_hi:[1,0]
	v_pk_add_f32 v[156:157], v[156:157], 1.0 op_sel_hi:[1,0]
	v_lshl_add_u64 v[128:129], v[128:129], 0, s[14:15]
	s_waitcnt lgkmcnt(4)
	v_sub_f32_e32 v131, v131, v186
	v_sub_f32_e32 v130, v130, v186
	v_pk_mul_f32 v[130:131], v[186:187], v[130:131] op_sel:[1,0]
	v_sub_f32_e32 v139, v171, v188
	v_sub_f32_e32 v138, v170, v188
	v_sub_f32_e32 v171, v173, v188
	v_sub_f32_e32 v170, v172, v188
	s_add_u32 s14, s2, s28
	v_sub_f32_e32 v133, v133, v186
	v_sub_f32_e32 v132, v132, v186
	v_pk_fma_f32 v[130:131], v[148:149], v[130:131], v[152:153]
	v_pk_mul_f32 v[170:171], v[188:189], v[170:171] op_sel:[1,0]
	s_addc_u32 s15, s3, s29
	v_pk_mul_f32 v[132:133], v[186:187], v[132:133] op_sel:[1,0]
	v_pk_fma_f32 v[190:191], v[150:151], v[170:171], v[154:155]
	v_cndmask_b32_e32 v171, v245, v131, vcc
	v_cndmask_b32_e32 v170, v245, v130, vcc
	v_lshlrev_b64 v[130:131], 2, v[194:195]
	v_pk_fma_f32 v[132:133], v[150:151], v[132:133], v[154:155]
	v_pk_mul_f32 v[138:139], v[188:189], v[138:139] op_sel:[1,0]
	v_lshl_add_u64 v[194:195], s[14:15], 0, v[130:131]
	s_mov_b32 s20, 0x10000
	s_add_i32 s14, s66, s4
	v_pk_fma_f32 v[138:139], v[148:149], v[138:139], v[152:153]
	v_cndmask_b32_e32 v172, v245, v132, vcc
	v_add_co_u32_e64 v132, s[18:19], s20, v194
	s_ashr_i32 s15, s14, 31
	v_cndmask_b32_e32 v173, v245, v133, vcc
	v_cndmask_b32_e32 v193, v245, v191, vcc
	v_cndmask_b32_e32 v192, v245, v190, vcc
	v_cndmask_b32_e32 v191, v245, v139, vcc
	v_cndmask_b32_e32 v190, v245, v138, vcc
	v_addc_co_u32_e64 v133, s[18:19], 0, v195, s[18:19]
	s_lshl_b64 s[14:15], s[14:15], 12
	global_store_dwordx4 v[194:195], v[170:173], off sc0 sc1 nt
	global_store_dwordx4 v[132:133], v[190:193], off sc0 sc1 nt
	s_waitcnt vmcnt(3)
	v_pk_fma_f32 v[132:133], v[158:159], v[172:173], v[142:143]
	v_pk_fma_f32 v[138:139], v[156:157], v[170:171], v[140:141]
	v_pk_fma_f32 v[172:173], v[156:157], v[190:191], v[140:141]
	v_lshl_add_u64 v[190:191], v[128:129], 0, s[14:15]
	v_pk_fma_f32 v[170:171], v[158:159], v[192:193], v[142:143]
	v_cvt_pk_bf16_f32 v138, v138, v139
	v_cvt_pk_bf16_f32 v139, v132, v133
	v_cvt_pk_bf16_f32 v132, v172, v173
	v_add_co_u32_e64 v192, s[18:19], s83, v190
	v_cvt_pk_bf16_f32 v133, v170, v171
	global_store_dwordx2 v[190:191], v[138:139], off
	ds_write_b128 v175, v[108:111]
	ds_write_b128 v175, v[116:119] offset:64
	ds_read_b128 v[108:111], v176
	ds_read_b128 v[116:119], v176 offset:1152
	ds_read2_b64 v[170:173], v181 offset0:16 offset1:24
	v_addc_co_u32_e64 v193, s[18:19], 0, v191, s[18:19]
	v_lshl_add_u64 v[196:197], v[194:195], 0, s[76:77]
	global_store_dwordx2 v[192:193], v[132:133], off
	s_waitcnt lgkmcnt(6)
	v_sub_f32_e32 v133, v135, v186
	v_sub_f32_e32 v132, v134, v186
	v_sub_f32_e32 v135, v137, v186
	v_sub_f32_e32 v134, v136, v186
	v_pk_mul_f32 v[134:135], v[186:187], v[134:135] op_sel:[1,0]
	v_pk_mul_f32 v[132:133], v[186:187], v[132:133] op_sel:[1,0]
	s_waitcnt lgkmcnt(5)
	v_sub_f32_e32 v137, v145, v188
	v_sub_f32_e32 v136, v144, v188
	v_sub_f32_e32 v139, v147, v188
	v_sub_f32_e32 v138, v146, v188
	v_pk_fma_f32 v[132:133], v[120:121], v[132:133], v[124:125]
	v_pk_fma_f32 v[134:135], v[122:123], v[134:135], v[126:127]
	v_pk_mul_f32 v[138:139], v[188:189], v[138:139] op_sel:[1,0]
	v_pk_mul_f32 v[136:137], v[188:189], v[136:137] op_sel:[1,0]
	v_pk_fma_f32 v[138:139], v[122:123], v[138:139], v[126:127]
	v_pk_fma_f32 v[136:137], v[120:121], v[136:137], v[124:125]
	v_cndmask_b32_e32 v135, v245, v135, vcc
	v_cndmask_b32_e32 v134, v245, v134, vcc
	v_cndmask_b32_e32 v133, v245, v133, vcc
	v_cndmask_b32_e32 v132, v245, v132, vcc
	v_cndmask_b32_e32 v139, v245, v139, vcc
	v_cndmask_b32_e32 v138, v245, v138, vcc
	v_cndmask_b32_e32 v137, v245, v137, vcc
	v_cndmask_b32_e32 v136, v245, v136, vcc
	global_store_dwordx4 v[194:195], v[132:135], off offset:512 sc0 sc1 nt
	global_store_dwordx4 v[196:197], v[136:139], off offset:512 sc0 sc1 nt
	s_waitcnt vmcnt(6)
	v_pk_fma_f32 v[134:135], v[162:163], v[134:135], v[114:115]
	v_pk_fma_f32 v[132:133], v[160:161], v[132:133], v[112:113]
	v_pk_fma_f32 v[138:139], v[162:163], v[138:139], v[114:115]
	v_pk_fma_f32 v[136:137], v[160:161], v[136:137], v[112:113]
	v_cvt_pk_bf16_f32 v132, v132, v133
	v_cvt_pk_bf16_f32 v133, v134, v135
	s_nop 0
	v_cvt_pk_bf16_f32 v134, v136, v137
	v_cvt_pk_bf16_f32 v135, v138, v139
	ds_write_b128 v175, v[100:103]
	ds_write_b128 v175, v[104:107] offset:64
	ds_read_b128 v[100:103], v176
	ds_read_b128 v[104:107], v176 offset:1152
	global_store_dwordx2 v[190:191], v[132:133], off offset:256
	global_store_dwordx2 v[192:193], v[134:135], off offset:256
	s_add_u32 s14, s2, s36
	s_addc_u32 s15, s3, s37
	s_waitcnt lgkmcnt(4)
	v_sub_f32_e32 v109, v109, v170
	v_sub_f32_e32 v108, v108, v170
	v_sub_f32_e32 v111, v111, v170
	v_sub_f32_e32 v110, v110, v170
	v_sub_f32_e32 v117, v117, v172
	v_sub_f32_e32 v116, v116, v172
	v_sub_f32_e32 v119, v119, v172
	v_sub_f32_e32 v118, v118, v172
	v_pk_mul_f32 v[110:111], v[170:171], v[110:111] op_sel:[1,0]
	v_pk_mul_f32 v[108:109], v[170:171], v[108:109] op_sel:[1,0]
	v_pk_mul_f32 v[118:119], v[172:173], v[118:119] op_sel:[1,0]
	v_pk_mul_f32 v[116:117], v[172:173], v[116:117] op_sel:[1,0]
	v_lshl_add_u64 v[132:133], s[14:15], 0, v[130:131]
	v_readlane_b32 s14, v254, 50
	v_pk_fma_f32 v[108:109], v[148:149], v[108:109], v[152:153]
	v_pk_fma_f32 v[110:111], v[150:151], v[110:111], v[154:155]
	v_pk_fma_f32 v[116:117], v[148:149], v[116:117], v[152:153]
	v_pk_fma_f32 v[118:119], v[150:151], v[118:119], v[154:155]
	v_add_co_u32_e64 v136, s[18:19], s20, v132
	v_readlane_b32 s15, v254, 51
	s_add_i32 s14, s66, s14
	v_cndmask_b32_e32 v111, v245, v111, vcc
	v_cndmask_b32_e32 v110, v245, v110, vcc
	v_cndmask_b32_e32 v109, v245, v109, vcc
	v_cndmask_b32_e32 v108, v245, v108, vcc
	v_cndmask_b32_e32 v119, v245, v119, vcc
	v_cndmask_b32_e32 v118, v245, v118, vcc
	v_cndmask_b32_e32 v117, v245, v117, vcc
	v_cndmask_b32_e32 v116, v245, v116, vcc
	v_addc_co_u32_e64 v137, s[18:19], 0, v133, s[18:19]
	s_ashr_i32 s15, s14, 31
	global_store_dwordx4 v[132:133], v[108:111], off sc0 sc1 nt
	global_store_dwordx4 v[136:137], v[116:119], off sc0 sc1 nt
	s_lshl_b64 s[14:15], s[14:15], 12
	v_pk_fma_f32 v[108:109], v[156:157], v[108:109], v[140:141]
	v_pk_fma_f32 v[118:119], v[158:159], v[118:119], v[142:143]
	v_pk_fma_f32 v[116:117], v[156:157], v[116:117], v[140:141]
	v_pk_fma_f32 v[110:111], v[158:159], v[110:111], v[142:143]
	v_cvt_pk_bf16_f32 v108, v108, v109
	v_lshl_add_u64 v[134:135], v[132:133], 0, s[76:77]
	v_cvt_pk_bf16_f32 v109, v110, v111
	v_cvt_pk_bf16_f32 v116, v116, v117
	v_cvt_pk_bf16_f32 v117, v118, v119
	v_lshl_add_u64 v[118:119], v[128:129], 0, s[14:15]
	global_store_dwordx2 v[118:119], v[108:109], off
	ds_write_b128 v175, v[92:95]
	ds_write_b128 v175, v[96:99] offset:64
	ds_read_b128 v[92:95], v176
	ds_read_b128 v[96:99], v176 offset:1152
	ds_read2_b64 v[108:111], v181 offset0:32 offset1:40
	v_add_co_u32_e64 v136, s[18:19], s83, v118
	s_nop 1
	v_addc_co_u32_e64 v137, s[18:19], 0, v119, s[18:19]
	global_store_dwordx2 v[136:137], v[116:117], off
	s_waitcnt lgkmcnt(6)
	v_sub_f32_e32 v101, v101, v170
	v_sub_f32_e32 v100, v100, v170
	v_sub_f32_e32 v103, v103, v170
	v_sub_f32_e32 v102, v102, v170
	v_pk_mul_f32 v[102:103], v[170:171], v[102:103] op_sel:[1,0]
	v_pk_mul_f32 v[100:101], v[170:171], v[100:101] op_sel:[1,0]
	s_waitcnt lgkmcnt(5)
	v_sub_f32_e32 v105, v105, v172
	v_sub_f32_e32 v104, v104, v172
	v_sub_f32_e32 v107, v107, v172
	v_sub_f32_e32 v106, v106, v172
	v_pk_fma_f32 v[100:101], v[120:121], v[100:101], v[124:125]
	v_pk_fma_f32 v[102:103], v[122:123], v[102:103], v[126:127]
	v_pk_mul_f32 v[106:107], v[172:173], v[106:107] op_sel:[1,0]
	v_pk_mul_f32 v[104:105], v[172:173], v[104:105] op_sel:[1,0]
	v_pk_fma_f32 v[106:107], v[122:123], v[106:107], v[126:127]
	v_pk_fma_f32 v[104:105], v[120:121], v[104:105], v[124:125]
	v_cndmask_b32_e32 v103, v245, v103, vcc
	v_cndmask_b32_e32 v102, v245, v102, vcc
	v_cndmask_b32_e32 v101, v245, v101, vcc
	v_cndmask_b32_e32 v100, v245, v100, vcc
	v_cndmask_b32_e32 v107, v245, v107, vcc
	v_cndmask_b32_e32 v106, v245, v106, vcc
	v_cndmask_b32_e32 v105, v245, v105, vcc
	v_cndmask_b32_e32 v104, v245, v104, vcc
	global_store_dwordx4 v[132:133], v[100:103], off offset:512 sc0 sc1 nt
	global_store_dwordx4 v[134:135], v[104:107], off offset:512 sc0 sc1 nt
	s_nop 0
	v_pk_fma_f32 v[100:101], v[160:161], v[100:101], v[112:113]
	v_pk_fma_f32 v[102:103], v[162:163], v[102:103], v[114:115]
	v_cvt_pk_bf16_f32 v100, v100, v101
	v_pk_fma_f32 v[106:107], v[162:163], v[106:107], v[114:115]
	v_cvt_pk_bf16_f32 v101, v102, v103
	v_pk_fma_f32 v[104:105], v[160:161], v[104:105], v[112:113]
	s_nop 0
	v_cvt_pk_bf16_f32 v102, v104, v105
	v_cvt_pk_bf16_f32 v103, v106, v107
	global_store_dwordx2 v[118:119], v[100:101], off offset:256
	global_store_dwordx2 v[136:137], v[102:103], off offset:256
	ds_write_b128 v175, v[84:87]
	ds_write_b128 v175, v[88:91] offset:64
	ds_read_b128 v[84:87], v176
	ds_read_b128 v[88:91], v176 offset:1152
	s_add_u32 s14, s2, s42
	s_addc_u32 s15, s3, s43
	s_waitcnt lgkmcnt(4)
	v_sub_f32_e32 v93, v93, v108
	v_sub_f32_e32 v92, v92, v108
	v_sub_f32_e32 v95, v95, v108
	v_sub_f32_e32 v94, v94, v108
	v_sub_f32_e32 v97, v97, v110
	v_sub_f32_e32 v96, v96, v110
	v_sub_f32_e32 v99, v99, v110
	v_sub_f32_e32 v98, v98, v110
	v_pk_mul_f32 v[94:95], v[108:109], v[94:95] op_sel:[1,0]
	v_pk_mul_f32 v[92:93], v[108:109], v[92:93] op_sel:[1,0]
	v_pk_mul_f32 v[98:99], v[110:111], v[98:99] op_sel:[1,0]
	v_pk_mul_f32 v[96:97], v[110:111], v[96:97] op_sel:[1,0]
	v_lshl_add_u64 v[100:101], s[14:15], 0, v[130:131]
	v_readlane_b32 s14, v254, 54
	v_pk_fma_f32 v[92:93], v[148:149], v[92:93], v[152:153]
	v_pk_fma_f32 v[94:95], v[150:151], v[94:95], v[154:155]
	v_pk_fma_f32 v[96:97], v[148:149], v[96:97], v[152:153]
	v_pk_fma_f32 v[98:99], v[150:151], v[98:99], v[154:155]
	v_add_co_u32_e64 v104, s[18:19], s20, v100
	v_readlane_b32 s15, v254, 55
	s_add_i32 s14, s66, s14
	v_cndmask_b32_e32 v95, v245, v95, vcc
	v_cndmask_b32_e32 v94, v245, v94, vcc
	v_cndmask_b32_e32 v93, v245, v93, vcc
	v_cndmask_b32_e32 v92, v245, v92, vcc
	v_cndmask_b32_e32 v99, v245, v99, vcc
	v_cndmask_b32_e32 v98, v245, v98, vcc
	v_cndmask_b32_e32 v97, v245, v97, vcc
	v_cndmask_b32_e32 v96, v245, v96, vcc
	v_addc_co_u32_e64 v105, s[18:19], 0, v101, s[18:19]
	s_ashr_i32 s15, s14, 31
	global_store_dwordx4 v[100:101], v[92:95], off sc0 sc1 nt
	global_store_dwordx4 v[104:105], v[96:99], off sc0 sc1 nt
	s_lshl_b64 s[14:15], s[14:15], 12
	v_pk_fma_f32 v[92:93], v[156:157], v[92:93], v[140:141]
	v_pk_fma_f32 v[98:99], v[158:159], v[98:99], v[142:143]
	v_pk_fma_f32 v[96:97], v[156:157], v[96:97], v[140:141]
	v_pk_fma_f32 v[94:95], v[158:159], v[94:95], v[142:143]
	v_cvt_pk_bf16_f32 v92, v92, v93
	v_lshl_add_u64 v[102:103], v[100:101], 0, s[76:77]
	v_cvt_pk_bf16_f32 v93, v94, v95
	v_cvt_pk_bf16_f32 v96, v96, v97
	v_cvt_pk_bf16_f32 v97, v98, v99
	v_lshl_add_u64 v[98:99], v[128:129], 0, s[14:15]
	global_store_dwordx2 v[98:99], v[92:93], off
	ds_write_b128 v175, v[76:79]
	ds_write_b128 v175, v[80:83] offset:64
	ds_read_b128 v[76:79], v176
	ds_read_b128 v[80:83], v176 offset:1152
	ds_read2_b64 v[92:95], v181 offset0:48 offset1:56
	v_add_co_u32_e64 v104, s[18:19], s83, v98
	s_nop 1
	v_addc_co_u32_e64 v105, s[18:19], 0, v99, s[18:19]
	global_store_dwordx2 v[104:105], v[96:97], off
	s_waitcnt lgkmcnt(6)
	v_sub_f32_e32 v85, v85, v108
	v_sub_f32_e32 v84, v84, v108
	v_sub_f32_e32 v87, v87, v108
	v_sub_f32_e32 v86, v86, v108
	v_pk_mul_f32 v[86:87], v[108:109], v[86:87] op_sel:[1,0]
	v_pk_mul_f32 v[84:85], v[108:109], v[84:85] op_sel:[1,0]
	s_waitcnt lgkmcnt(5)
	v_sub_f32_e32 v89, v89, v110
	v_sub_f32_e32 v88, v88, v110
	v_sub_f32_e32 v91, v91, v110
	v_sub_f32_e32 v90, v90, v110
	v_pk_fma_f32 v[84:85], v[120:121], v[84:85], v[124:125]
	v_pk_fma_f32 v[86:87], v[122:123], v[86:87], v[126:127]
	v_pk_mul_f32 v[90:91], v[110:111], v[90:91] op_sel:[1,0]
	v_pk_mul_f32 v[88:89], v[110:111], v[88:89] op_sel:[1,0]
	v_pk_fma_f32 v[90:91], v[122:123], v[90:91], v[126:127]
	v_pk_fma_f32 v[88:89], v[120:121], v[88:89], v[124:125]
	v_cndmask_b32_e32 v87, v245, v87, vcc
	v_cndmask_b32_e32 v86, v245, v86, vcc
	v_cndmask_b32_e32 v85, v245, v85, vcc
	v_cndmask_b32_e32 v84, v245, v84, vcc
	v_cndmask_b32_e32 v91, v245, v91, vcc
	v_cndmask_b32_e32 v90, v245, v90, vcc
	v_cndmask_b32_e32 v89, v245, v89, vcc
	v_cndmask_b32_e32 v88, v245, v88, vcc
	global_store_dwordx4 v[100:101], v[84:87], off offset:512 sc0 sc1 nt
	global_store_dwordx4 v[102:103], v[88:91], off offset:512 sc0 sc1 nt
	s_nop 0
	v_pk_fma_f32 v[86:87], v[162:163], v[86:87], v[114:115]
	v_pk_fma_f32 v[84:85], v[160:161], v[84:85], v[112:113]
	v_pk_fma_f32 v[90:91], v[162:163], v[90:91], v[114:115]
	v_pk_fma_f32 v[88:89], v[160:161], v[88:89], v[112:113]
	v_cvt_pk_bf16_f32 v84, v84, v85
	v_cvt_pk_bf16_f32 v85, v86, v87
	s_nop 0
	v_cvt_pk_bf16_f32 v86, v88, v89
	v_cvt_pk_bf16_f32 v87, v90, v91
	ds_write_b128 v175, v[68:71]
	ds_write_b128 v175, v[72:75] offset:64
	ds_read_b128 v[68:71], v176
	ds_read_b128 v[72:75], v176 offset:1152
	global_store_dwordx2 v[98:99], v[84:85], off offset:256
	global_store_dwordx2 v[104:105], v[86:87], off offset:256
	s_add_u32 s14, s2, s48
	s_addc_u32 s15, s3, s49
	s_waitcnt lgkmcnt(4)
	v_sub_f32_e32 v77, v77, v92
	v_sub_f32_e32 v76, v76, v92
	v_sub_f32_e32 v79, v79, v92
	v_sub_f32_e32 v78, v78, v92
	v_sub_f32_e32 v81, v81, v94
	v_sub_f32_e32 v80, v80, v94
	v_sub_f32_e32 v83, v83, v94
	v_sub_f32_e32 v82, v82, v94
	v_pk_mul_f32 v[78:79], v[92:93], v[78:79] op_sel:[1,0]
	v_pk_mul_f32 v[76:77], v[92:93], v[76:77] op_sel:[1,0]
	v_pk_mul_f32 v[82:83], v[94:95], v[82:83] op_sel:[1,0]
	v_pk_mul_f32 v[80:81], v[94:95], v[80:81] op_sel:[1,0]
	v_lshl_add_u64 v[84:85], s[14:15], 0, v[130:131]
	v_readlane_b32 s14, v254, 58
	v_pk_fma_f32 v[76:77], v[148:149], v[76:77], v[152:153]
	v_pk_fma_f32 v[78:79], v[150:151], v[78:79], v[154:155]
	v_pk_fma_f32 v[80:81], v[148:149], v[80:81], v[152:153]
	v_pk_fma_f32 v[82:83], v[150:151], v[82:83], v[154:155]
	v_add_co_u32_e64 v88, s[18:19], s20, v84
	v_readlane_b32 s15, v254, 59
	s_add_i32 s14, s66, s14
	v_cndmask_b32_e32 v79, v245, v79, vcc
	v_cndmask_b32_e32 v78, v245, v78, vcc
	v_cndmask_b32_e32 v77, v245, v77, vcc
	v_cndmask_b32_e32 v76, v245, v76, vcc
	v_cndmask_b32_e32 v83, v245, v83, vcc
	v_cndmask_b32_e32 v82, v245, v82, vcc
	v_cndmask_b32_e32 v81, v245, v81, vcc
	v_cndmask_b32_e32 v80, v245, v80, vcc
	v_addc_co_u32_e64 v89, s[18:19], 0, v85, s[18:19]
	s_ashr_i32 s15, s14, 31
	global_store_dwordx4 v[84:85], v[76:79], off sc0 sc1 nt
	global_store_dwordx4 v[88:89], v[80:83], off sc0 sc1 nt
	s_lshl_b64 s[14:15], s[14:15], 12
	v_pk_fma_f32 v[76:77], v[156:157], v[76:77], v[140:141]
	v_pk_fma_f32 v[82:83], v[158:159], v[82:83], v[142:143]
	v_pk_fma_f32 v[80:81], v[156:157], v[80:81], v[140:141]
	v_pk_fma_f32 v[78:79], v[158:159], v[78:79], v[142:143]
	v_cvt_pk_bf16_f32 v76, v76, v77
	v_lshl_add_u64 v[86:87], v[84:85], 0, s[76:77]
	v_cvt_pk_bf16_f32 v77, v78, v79
	v_cvt_pk_bf16_f32 v80, v80, v81
	v_cvt_pk_bf16_f32 v81, v82, v83
	v_lshl_add_u64 v[82:83], v[128:129], 0, s[14:15]
	global_store_dwordx2 v[82:83], v[76:77], off
	ds_write_b128 v175, v[60:63]
	ds_write_b128 v175, v[64:67] offset:64
	ds_read_b128 v[60:63], v176
	ds_read_b128 v[64:67], v176 offset:1152
	ds_read2_b64 v[76:79], v181 offset0:128 offset1:136
	v_add_co_u32_e64 v88, s[18:19], s83, v82
	s_nop 1
	v_addc_co_u32_e64 v89, s[18:19], 0, v83, s[18:19]
	global_store_dwordx2 v[88:89], v[80:81], off
	s_waitcnt lgkmcnt(6)
	v_sub_f32_e32 v69, v69, v92
	v_sub_f32_e32 v68, v68, v92
	v_sub_f32_e32 v71, v71, v92
	v_sub_f32_e32 v70, v70, v92
	v_pk_mul_f32 v[70:71], v[92:93], v[70:71] op_sel:[1,0]
	v_pk_mul_f32 v[68:69], v[92:93], v[68:69] op_sel:[1,0]
	s_waitcnt lgkmcnt(5)
	v_sub_f32_e32 v73, v73, v94
	v_sub_f32_e32 v72, v72, v94
	v_sub_f32_e32 v75, v75, v94
	v_sub_f32_e32 v74, v74, v94
	v_pk_fma_f32 v[68:69], v[120:121], v[68:69], v[124:125]
	v_pk_fma_f32 v[70:71], v[122:123], v[70:71], v[126:127]
	v_pk_mul_f32 v[74:75], v[94:95], v[74:75] op_sel:[1,0]
	v_pk_mul_f32 v[72:73], v[94:95], v[72:73] op_sel:[1,0]
	v_pk_fma_f32 v[74:75], v[122:123], v[74:75], v[126:127]
	v_pk_fma_f32 v[72:73], v[120:121], v[72:73], v[124:125]
	v_cndmask_b32_e32 v71, v245, v71, vcc
	v_cndmask_b32_e32 v70, v245, v70, vcc
	v_cndmask_b32_e32 v69, v245, v69, vcc
	v_cndmask_b32_e32 v68, v245, v68, vcc
	v_cndmask_b32_e32 v75, v245, v75, vcc
	v_cndmask_b32_e32 v74, v245, v74, vcc
	v_cndmask_b32_e32 v73, v245, v73, vcc
	v_cndmask_b32_e32 v72, v245, v72, vcc
	global_store_dwordx4 v[84:85], v[68:71], off offset:512 sc0 sc1 nt
	global_store_dwordx4 v[86:87], v[72:75], off offset:512 sc0 sc1 nt
	s_nop 0
	v_pk_fma_f32 v[68:69], v[160:161], v[68:69], v[112:113]
	v_pk_fma_f32 v[70:71], v[162:163], v[70:71], v[114:115]
	v_cvt_pk_bf16_f32 v68, v68, v69
	v_pk_fma_f32 v[74:75], v[162:163], v[74:75], v[114:115]
	v_cvt_pk_bf16_f32 v69, v70, v71
	v_pk_fma_f32 v[72:73], v[160:161], v[72:73], v[112:113]
	s_nop 0
	v_cvt_pk_bf16_f32 v70, v72, v73
	v_cvt_pk_bf16_f32 v71, v74, v75
	global_store_dwordx2 v[82:83], v[68:69], off offset:256
	global_store_dwordx2 v[88:89], v[70:71], off offset:256
	ds_write_b128 v175, v[52:55]
	ds_write_b128 v175, v[56:59] offset:64
	ds_read_b128 v[52:55], v176
	ds_read_b128 v[56:59], v176 offset:1152
	s_add_u32 s14, s2, s54
	s_addc_u32 s15, s3, s55
	s_waitcnt lgkmcnt(4)
	v_sub_f32_e32 v61, v61, v76
	v_sub_f32_e32 v60, v60, v76
	v_sub_f32_e32 v63, v63, v76
	v_sub_f32_e32 v62, v62, v76
	v_sub_f32_e32 v65, v65, v78
	v_sub_f32_e32 v64, v64, v78
	v_sub_f32_e32 v67, v67, v78
	v_sub_f32_e32 v66, v66, v78
	v_pk_mul_f32 v[62:63], v[76:77], v[62:63] op_sel:[1,0]
	v_pk_mul_f32 v[60:61], v[76:77], v[60:61] op_sel:[1,0]
	v_pk_mul_f32 v[66:67], v[78:79], v[66:67] op_sel:[1,0]
	v_pk_mul_f32 v[64:65], v[78:79], v[64:65] op_sel:[1,0]
	v_lshl_add_u64 v[68:69], s[14:15], 0, v[130:131]
	v_readlane_b32 s14, v254, 62
	v_pk_fma_f32 v[60:61], v[148:149], v[60:61], v[152:153]
	v_pk_fma_f32 v[62:63], v[150:151], v[62:63], v[154:155]
	v_pk_fma_f32 v[64:65], v[148:149], v[64:65], v[152:153]
	v_pk_fma_f32 v[66:67], v[150:151], v[66:67], v[154:155]
	v_add_co_u32_e64 v72, s[18:19], s20, v68
	v_readlane_b32 s15, v254, 63
	s_add_i32 s14, s66, s14
	v_cndmask_b32_e32 v63, v245, v63, vcc
	v_cndmask_b32_e32 v62, v245, v62, vcc
	v_cndmask_b32_e32 v61, v245, v61, vcc
	v_cndmask_b32_e32 v60, v245, v60, vcc
	v_cndmask_b32_e32 v67, v245, v67, vcc
	v_cndmask_b32_e32 v66, v245, v66, vcc
	v_cndmask_b32_e32 v65, v245, v65, vcc
	v_cndmask_b32_e32 v64, v245, v64, vcc
	v_addc_co_u32_e64 v73, s[18:19], 0, v69, s[18:19]
	s_ashr_i32 s15, s14, 31
	global_store_dwordx4 v[68:69], v[60:63], off sc0 sc1 nt
	global_store_dwordx4 v[72:73], v[64:67], off sc0 sc1 nt
	s_lshl_b64 s[14:15], s[14:15], 12
	v_pk_fma_f32 v[60:61], v[156:157], v[60:61], v[140:141]
	v_pk_fma_f32 v[66:67], v[158:159], v[66:67], v[142:143]
	v_pk_fma_f32 v[64:65], v[156:157], v[64:65], v[140:141]
	v_pk_fma_f32 v[62:63], v[158:159], v[62:63], v[142:143]
	v_cvt_pk_bf16_f32 v60, v60, v61
	v_lshl_add_u64 v[70:71], v[68:69], 0, s[76:77]
	v_cvt_pk_bf16_f32 v61, v62, v63
	v_cvt_pk_bf16_f32 v64, v64, v65
	v_cvt_pk_bf16_f32 v65, v66, v67
	v_lshl_add_u64 v[66:67], v[128:129], 0, s[14:15]
	global_store_dwordx2 v[66:67], v[60:61], off
	ds_write_b128 v175, v[44:47]
	ds_write_b128 v175, v[48:51] offset:64
	ds_read_b128 v[44:47], v176
	ds_read_b128 v[48:51], v176 offset:1152
	ds_read2_b64 v[60:63], v181 offset0:144 offset1:152
	v_add_co_u32_e64 v72, s[18:19], s83, v66
	s_nop 1
	v_addc_co_u32_e64 v73, s[18:19], 0, v67, s[18:19]
	global_store_dwordx2 v[72:73], v[64:65], off
	s_waitcnt lgkmcnt(6)
	v_sub_f32_e32 v53, v53, v76
	v_sub_f32_e32 v52, v52, v76
	v_sub_f32_e32 v55, v55, v76
	v_sub_f32_e32 v54, v54, v76
	v_pk_mul_f32 v[54:55], v[76:77], v[54:55] op_sel:[1,0]
	v_pk_mul_f32 v[52:53], v[76:77], v[52:53] op_sel:[1,0]
	s_waitcnt lgkmcnt(5)
	v_sub_f32_e32 v57, v57, v78
	v_sub_f32_e32 v56, v56, v78
	v_sub_f32_e32 v59, v59, v78
	v_sub_f32_e32 v58, v58, v78
	v_pk_fma_f32 v[52:53], v[120:121], v[52:53], v[124:125]
	v_pk_fma_f32 v[54:55], v[122:123], v[54:55], v[126:127]
	v_pk_mul_f32 v[58:59], v[78:79], v[58:59] op_sel:[1,0]
	v_pk_mul_f32 v[56:57], v[78:79], v[56:57] op_sel:[1,0]
	v_pk_fma_f32 v[58:59], v[122:123], v[58:59], v[126:127]
	v_pk_fma_f32 v[56:57], v[120:121], v[56:57], v[124:125]
	v_cndmask_b32_e32 v55, v245, v55, vcc
	v_cndmask_b32_e32 v54, v245, v54, vcc
	v_cndmask_b32_e32 v53, v245, v53, vcc
	v_cndmask_b32_e32 v52, v245, v52, vcc
	v_cndmask_b32_e32 v59, v245, v59, vcc
	v_cndmask_b32_e32 v58, v245, v58, vcc
	v_cndmask_b32_e32 v57, v245, v57, vcc
	v_cndmask_b32_e32 v56, v245, v56, vcc
	global_store_dwordx4 v[68:69], v[52:55], off offset:512 sc0 sc1 nt
	global_store_dwordx4 v[70:71], v[56:59], off offset:512 sc0 sc1 nt
	s_nop 0
	v_pk_fma_f32 v[54:55], v[162:163], v[54:55], v[114:115]
	v_pk_fma_f32 v[52:53], v[160:161], v[52:53], v[112:113]
	v_pk_fma_f32 v[58:59], v[162:163], v[58:59], v[114:115]
	v_pk_fma_f32 v[56:57], v[160:161], v[56:57], v[112:113]
	v_cvt_pk_bf16_f32 v52, v52, v53
	v_cvt_pk_bf16_f32 v53, v54, v55
	s_nop 0
	v_cvt_pk_bf16_f32 v54, v56, v57
	v_cvt_pk_bf16_f32 v55, v58, v59
	ds_write_b128 v175, v[36:39]
	ds_write_b128 v175, v[40:43] offset:64
	ds_read_b128 v[36:39], v176
	ds_read_b128 v[40:43], v176 offset:1152
	global_store_dwordx2 v[66:67], v[52:53], off offset:256
	global_store_dwordx2 v[72:73], v[54:55], off offset:256
	s_add_u32 s14, s2, s60
	s_addc_u32 s15, s3, s61
	s_waitcnt lgkmcnt(4)
	v_sub_f32_e32 v45, v45, v60
	v_sub_f32_e32 v44, v44, v60
	v_sub_f32_e32 v47, v47, v60
	v_sub_f32_e32 v46, v46, v60
	v_sub_f32_e32 v49, v49, v62
	v_sub_f32_e32 v48, v48, v62
	v_sub_f32_e32 v51, v51, v62
	v_sub_f32_e32 v50, v50, v62
	v_pk_mul_f32 v[46:47], v[60:61], v[46:47] op_sel:[1,0]
	v_pk_mul_f32 v[44:45], v[60:61], v[44:45] op_sel:[1,0]
	v_pk_mul_f32 v[50:51], v[62:63], v[50:51] op_sel:[1,0]
	v_pk_mul_f32 v[48:49], v[62:63], v[48:49] op_sel:[1,0]
	v_lshl_add_u64 v[52:53], s[14:15], 0, v[130:131]
	v_pk_fma_f32 v[44:45], v[148:149], v[44:45], v[152:153]
	v_pk_fma_f32 v[46:47], v[150:151], v[46:47], v[154:155]
	v_pk_fma_f32 v[48:49], v[148:149], v[48:49], v[152:153]
	v_pk_fma_f32 v[50:51], v[150:151], v[50:51], v[154:155]
	v_add_co_u32_e64 v56, s[18:19], s20, v52
	s_add_i32 s14, s66, s58
	v_cndmask_b32_e32 v47, v245, v47, vcc
	v_cndmask_b32_e32 v46, v245, v46, vcc
	v_cndmask_b32_e32 v45, v245, v45, vcc
	v_cndmask_b32_e32 v44, v245, v44, vcc
	v_cndmask_b32_e32 v51, v245, v51, vcc
	v_cndmask_b32_e32 v50, v245, v50, vcc
	v_cndmask_b32_e32 v49, v245, v49, vcc
	v_cndmask_b32_e32 v48, v245, v48, vcc
	v_addc_co_u32_e64 v57, s[18:19], 0, v53, s[18:19]
	s_ashr_i32 s15, s14, 31
	global_store_dwordx4 v[52:53], v[44:47], off sc0 sc1 nt
	global_store_dwordx4 v[56:57], v[48:51], off sc0 sc1 nt
	s_lshl_b64 s[14:15], s[14:15], 12
	v_pk_fma_f32 v[44:45], v[156:157], v[44:45], v[140:141]
	v_pk_fma_f32 v[50:51], v[158:159], v[50:51], v[142:143]
	v_pk_fma_f32 v[48:49], v[156:157], v[48:49], v[140:141]
	v_pk_fma_f32 v[46:47], v[158:159], v[46:47], v[142:143]
	v_cvt_pk_bf16_f32 v44, v44, v45
	v_lshl_add_u64 v[54:55], v[52:53], 0, s[76:77]
	v_cvt_pk_bf16_f32 v45, v46, v47
	v_cvt_pk_bf16_f32 v48, v48, v49
	v_cvt_pk_bf16_f32 v49, v50, v51
	v_lshl_add_u64 v[50:51], v[128:129], 0, s[14:15]
	global_store_dwordx2 v[50:51], v[44:45], off
	ds_write_b128 v175, v[28:31]
	ds_write_b128 v175, v[32:35] offset:64
	ds_read_b128 v[28:31], v176
	ds_read_b128 v[32:35], v176 offset:1152
	ds_read2_b64 v[44:47], v181 offset0:160 offset1:168
	v_add_co_u32_e64 v56, s[18:19], s83, v50
	s_nop 1
	v_addc_co_u32_e64 v57, s[18:19], 0, v51, s[18:19]
	global_store_dwordx2 v[56:57], v[48:49], off
	s_waitcnt lgkmcnt(6)
	v_sub_f32_e32 v37, v37, v60
	v_sub_f32_e32 v36, v36, v60
	v_sub_f32_e32 v39, v39, v60
	v_sub_f32_e32 v38, v38, v60
	v_pk_mul_f32 v[38:39], v[60:61], v[38:39] op_sel:[1,0]
	v_pk_mul_f32 v[36:37], v[60:61], v[36:37] op_sel:[1,0]
	s_waitcnt lgkmcnt(5)
	v_sub_f32_e32 v41, v41, v62
	v_sub_f32_e32 v40, v40, v62
	v_sub_f32_e32 v43, v43, v62
	v_sub_f32_e32 v42, v42, v62
	v_pk_fma_f32 v[36:37], v[120:121], v[36:37], v[124:125]
	v_pk_fma_f32 v[38:39], v[122:123], v[38:39], v[126:127]
	v_pk_mul_f32 v[42:43], v[62:63], v[42:43] op_sel:[1,0]
	v_pk_mul_f32 v[40:41], v[62:63], v[40:41] op_sel:[1,0]
	v_pk_fma_f32 v[42:43], v[122:123], v[42:43], v[126:127]
	v_pk_fma_f32 v[40:41], v[120:121], v[40:41], v[124:125]
	v_cndmask_b32_e32 v39, v245, v39, vcc
	v_cndmask_b32_e32 v38, v245, v38, vcc
	v_cndmask_b32_e32 v37, v245, v37, vcc
	v_cndmask_b32_e32 v36, v245, v36, vcc
	v_cndmask_b32_e32 v43, v245, v43, vcc
	v_cndmask_b32_e32 v42, v245, v42, vcc
	v_cndmask_b32_e32 v41, v245, v41, vcc
	v_cndmask_b32_e32 v40, v245, v40, vcc
	global_store_dwordx4 v[52:53], v[36:39], off offset:512 sc0 sc1 nt
	global_store_dwordx4 v[54:55], v[40:43], off offset:512 sc0 sc1 nt
	s_nop 0
	v_pk_fma_f32 v[36:37], v[160:161], v[36:37], v[112:113]
	v_pk_fma_f32 v[38:39], v[162:163], v[38:39], v[114:115]
	v_cvt_pk_bf16_f32 v36, v36, v37
	v_pk_fma_f32 v[42:43], v[162:163], v[42:43], v[114:115]
	v_cvt_pk_bf16_f32 v37, v38, v39
	v_pk_fma_f32 v[40:41], v[160:161], v[40:41], v[112:113]
	s_nop 0
	v_cvt_pk_bf16_f32 v38, v40, v41
	v_cvt_pk_bf16_f32 v39, v42, v43
	global_store_dwordx2 v[50:51], v[36:37], off offset:256
	global_store_dwordx2 v[56:57], v[38:39], off offset:256
	ds_write_b128 v175, v[20:23]
	ds_write_b128 v175, v[24:27] offset:64
	ds_read_b128 v[20:23], v176
	ds_read_b128 v[24:27], v176 offset:1152
	s_add_u32 s14, s2, s70
	s_addc_u32 s15, s3, s71
	s_waitcnt lgkmcnt(4)
	v_sub_f32_e32 v29, v29, v44
	v_sub_f32_e32 v28, v28, v44
	v_sub_f32_e32 v31, v31, v44
	v_sub_f32_e32 v30, v30, v44
	v_sub_f32_e32 v33, v33, v46
	v_sub_f32_e32 v32, v32, v46
	v_sub_f32_e32 v35, v35, v46
	v_sub_f32_e32 v34, v34, v46
	v_pk_mul_f32 v[30:31], v[44:45], v[30:31] op_sel:[1,0]
	v_pk_mul_f32 v[28:29], v[44:45], v[28:29] op_sel:[1,0]
	v_pk_mul_f32 v[34:35], v[46:47], v[34:35] op_sel:[1,0]
	v_pk_mul_f32 v[32:33], v[46:47], v[32:33] op_sel:[1,0]
	v_lshl_add_u64 v[36:37], s[14:15], 0, v[130:131]
	v_pk_fma_f32 v[28:29], v[148:149], v[28:29], v[152:153]
	v_pk_fma_f32 v[30:31], v[150:151], v[30:31], v[154:155]
	v_pk_fma_f32 v[32:33], v[148:149], v[32:33], v[152:153]
	v_pk_fma_f32 v[34:35], v[150:151], v[34:35], v[154:155]
	v_add_co_u32_e64 v40, s[18:19], s20, v36
	s_add_i32 s14, s66, s68
	v_cndmask_b32_e32 v31, v245, v31, vcc
	v_cndmask_b32_e32 v30, v245, v30, vcc
	v_cndmask_b32_e32 v29, v245, v29, vcc
	v_cndmask_b32_e32 v28, v245, v28, vcc
	v_cndmask_b32_e32 v35, v245, v35, vcc
	v_cndmask_b32_e32 v34, v245, v34, vcc
	v_cndmask_b32_e32 v33, v245, v33, vcc
	v_cndmask_b32_e32 v32, v245, v32, vcc
	v_addc_co_u32_e64 v41, s[18:19], 0, v37, s[18:19]
	s_ashr_i32 s15, s14, 31
	global_store_dwordx4 v[36:37], v[28:31], off sc0 sc1 nt
	global_store_dwordx4 v[40:41], v[32:35], off sc0 sc1 nt
	s_lshl_b64 s[14:15], s[14:15], 12
	v_pk_fma_f32 v[28:29], v[156:157], v[28:29], v[140:141]
	v_pk_fma_f32 v[34:35], v[158:159], v[34:35], v[142:143]
	v_pk_fma_f32 v[32:33], v[156:157], v[32:33], v[140:141]
	v_pk_fma_f32 v[30:31], v[158:159], v[30:31], v[142:143]
	v_cvt_pk_bf16_f32 v28, v28, v29
	v_lshl_add_u64 v[38:39], v[36:37], 0, s[76:77]
	v_cvt_pk_bf16_f32 v29, v30, v31
	v_cvt_pk_bf16_f32 v32, v32, v33
	v_cvt_pk_bf16_f32 v33, v34, v35
	v_lshl_add_u64 v[34:35], v[128:129], 0, s[14:15]
	global_store_dwordx2 v[34:35], v[28:29], off
	ds_write_b128 v175, v[12:15]
	ds_write_b128 v175, v[16:19] offset:64
	ds_read_b128 v[12:15], v176
	ds_read_b128 v[16:19], v176 offset:1152
	ds_read2_b64 v[28:31], v181 offset0:176 offset1:184
	v_add_co_u32_e64 v40, s[18:19], s83, v34
	s_nop 1
	v_addc_co_u32_e64 v41, s[18:19], 0, v35, s[18:19]
	global_store_dwordx2 v[40:41], v[32:33], off
	s_waitcnt lgkmcnt(6)
	v_sub_f32_e32 v21, v21, v44
	v_sub_f32_e32 v20, v20, v44
	v_sub_f32_e32 v23, v23, v44
	v_sub_f32_e32 v22, v22, v44
	v_pk_mul_f32 v[22:23], v[44:45], v[22:23] op_sel:[1,0]
	v_pk_mul_f32 v[20:21], v[44:45], v[20:21] op_sel:[1,0]
	s_waitcnt lgkmcnt(5)
	v_sub_f32_e32 v25, v25, v46
	v_sub_f32_e32 v24, v24, v46
	v_sub_f32_e32 v27, v27, v46
	v_sub_f32_e32 v26, v26, v46
	v_pk_fma_f32 v[20:21], v[120:121], v[20:21], v[124:125]
	v_pk_fma_f32 v[22:23], v[122:123], v[22:23], v[126:127]
	v_pk_mul_f32 v[26:27], v[46:47], v[26:27] op_sel:[1,0]
	v_pk_mul_f32 v[24:25], v[46:47], v[24:25] op_sel:[1,0]
	v_pk_fma_f32 v[26:27], v[122:123], v[26:27], v[126:127]
	v_pk_fma_f32 v[24:25], v[120:121], v[24:25], v[124:125]
	v_cndmask_b32_e32 v23, v245, v23, vcc
	v_cndmask_b32_e32 v22, v245, v22, vcc
	v_cndmask_b32_e32 v21, v245, v21, vcc
	v_cndmask_b32_e32 v20, v245, v20, vcc
	v_cndmask_b32_e32 v27, v245, v27, vcc
	v_cndmask_b32_e32 v26, v245, v26, vcc
	v_cndmask_b32_e32 v25, v245, v25, vcc
	v_cndmask_b32_e32 v24, v245, v24, vcc
	global_store_dwordx4 v[36:37], v[20:23], off offset:512 sc0 sc1 nt
	global_store_dwordx4 v[38:39], v[24:27], off offset:512 sc0 sc1 nt
	s_nop 0
	v_pk_fma_f32 v[22:23], v[162:163], v[22:23], v[114:115]
	v_pk_fma_f32 v[20:21], v[160:161], v[20:21], v[112:113]
	v_pk_fma_f32 v[26:27], v[162:163], v[26:27], v[114:115]
	v_pk_fma_f32 v[24:25], v[160:161], v[24:25], v[112:113]
	v_cvt_pk_bf16_f32 v20, v20, v21
	v_cvt_pk_bf16_f32 v21, v22, v23
	s_nop 0
	v_cvt_pk_bf16_f32 v22, v24, v25
	v_cvt_pk_bf16_f32 v23, v26, v27
	ds_write_b128 v175, v[4:7]
	ds_write_b128 v175, v[8:11] offset:64
	ds_read_b128 v[4:7], v176
	ds_read_b128 v[8:11], v176 offset:1152
	global_store_dwordx2 v[34:35], v[20:21], off offset:256
	global_store_dwordx2 v[40:41], v[22:23], off offset:256
	s_add_u32 s2, s2, s96
	s_addc_u32 s3, s3, s97
	s_waitcnt lgkmcnt(4)
	v_sub_f32_e32 v13, v13, v28
	v_sub_f32_e32 v12, v12, v28
	v_sub_f32_e32 v15, v15, v28
	v_sub_f32_e32 v14, v14, v28
	v_sub_f32_e32 v17, v17, v30
	v_sub_f32_e32 v16, v16, v30
	v_sub_f32_e32 v19, v19, v30
	v_sub_f32_e32 v18, v18, v30
	v_pk_mul_f32 v[14:15], v[28:29], v[14:15] op_sel:[1,0]
	v_pk_mul_f32 v[12:13], v[28:29], v[12:13] op_sel:[1,0]
	v_pk_mul_f32 v[18:19], v[30:31], v[18:19] op_sel:[1,0]
	v_pk_mul_f32 v[16:17], v[30:31], v[16:17] op_sel:[1,0]
	v_lshl_add_u64 v[20:21], s[2:3], 0, v[130:131]
	v_pk_fma_f32 v[12:13], v[148:149], v[12:13], v[152:153]
	v_pk_fma_f32 v[14:15], v[150:151], v[14:15], v[154:155]
	v_pk_fma_f32 v[16:17], v[148:149], v[16:17], v[152:153]
	v_pk_fma_f32 v[18:19], v[150:151], v[18:19], v[154:155]
	v_add_co_u32_e64 v24, s[18:19], s20, v20
	s_add_i32 s2, s66, s44
	v_cndmask_b32_e32 v15, v245, v15, vcc
	v_cndmask_b32_e32 v14, v245, v14, vcc
	v_cndmask_b32_e32 v13, v245, v13, vcc
	v_cndmask_b32_e32 v12, v245, v12, vcc
	v_cndmask_b32_e32 v19, v245, v19, vcc
	v_cndmask_b32_e32 v18, v245, v18, vcc
	v_cndmask_b32_e32 v17, v245, v17, vcc
	v_cndmask_b32_e32 v16, v245, v16, vcc
	v_addc_co_u32_e64 v25, s[18:19], 0, v21, s[18:19]
	s_ashr_i32 s3, s2, 31
	global_store_dwordx4 v[20:21], v[12:15], off sc0 sc1 nt
	global_store_dwordx4 v[24:25], v[16:19], off sc0 sc1 nt
	s_lshl_b64 s[2:3], s[2:3], 12
	v_pk_fma_f32 v[14:15], v[158:159], v[14:15], v[142:143]
	v_pk_fma_f32 v[12:13], v[156:157], v[12:13], v[140:141]
	v_pk_fma_f32 v[16:17], v[156:157], v[16:17], v[140:141]
	v_cvt_pk_bf16_f32 v12, v12, v13
	v_cvt_pk_bf16_f32 v13, v14, v15
	v_pk_fma_f32 v[18:19], v[158:159], v[18:19], v[142:143]
	v_cvt_pk_bf16_f32 v14, v16, v17
	v_lshl_add_u64 v[16:17], v[128:129], 0, s[2:3]
	v_cvt_pk_bf16_f32 v15, v18, v19
	global_store_dwordx2 v[16:17], v[12:13], off
	v_add_co_u32_e64 v12, s[18:19], s83, v16
	v_lshl_add_u64 v[22:23], v[20:21], 0, s[76:77]
	s_nop 0
	v_addc_co_u32_e64 v13, s[18:19], 0, v17, s[18:19]
	global_store_dwordx2 v[12:13], v[14:15], off
	s_waitcnt lgkmcnt(1)
	v_sub_f32_e32 v5, v5, v28
	v_sub_f32_e32 v4, v4, v28
	v_sub_f32_e32 v7, v7, v28
	v_sub_f32_e32 v6, v6, v28
	v_pk_mul_f32 v[6:7], v[28:29], v[6:7] op_sel:[1,0]
	v_pk_mul_f32 v[4:5], v[28:29], v[4:5] op_sel:[1,0]
	s_waitcnt lgkmcnt(0)
	v_sub_f32_e32 v9, v9, v30
	v_sub_f32_e32 v8, v8, v30
	v_sub_f32_e32 v11, v11, v30
	v_sub_f32_e32 v10, v10, v30
	v_pk_fma_f32 v[4:5], v[120:121], v[4:5], v[124:125]
	v_pk_fma_f32 v[6:7], v[122:123], v[6:7], v[126:127]
	v_pk_mul_f32 v[10:11], v[30:31], v[10:11] op_sel:[1,0]
	v_pk_mul_f32 v[8:9], v[30:31], v[8:9] op_sel:[1,0]
	v_pk_fma_f32 v[10:11], v[122:123], v[10:11], v[126:127]
	v_pk_fma_f32 v[8:9], v[120:121], v[8:9], v[124:125]
	v_cndmask_b32_e32 v7, v245, v7, vcc
	v_cndmask_b32_e32 v6, v245, v6, vcc
	v_cndmask_b32_e32 v5, v245, v5, vcc
	v_cndmask_b32_e32 v4, v245, v4, vcc
	v_cndmask_b32_e32 v11, v245, v11, vcc
	v_cndmask_b32_e32 v10, v245, v10, vcc
	v_cndmask_b32_e32 v9, v245, v9, vcc
	v_cndmask_b32_e32 v8, v245, v8, vcc
	global_store_dwordx4 v[20:21], v[4:7], off offset:512 sc0 sc1 nt
	global_store_dwordx4 v[22:23], v[8:11], off offset:512 sc0 sc1 nt
	s_and_b64 vcc, exec, s[16:17]
	v_pk_fma_f32 v[4:5], v[160:161], v[4:5], v[112:113]
	v_pk_fma_f32 v[6:7], v[162:163], v[6:7], v[114:115]
	v_cvt_pk_bf16_f32 v4, v4, v5
	v_pk_fma_f32 v[10:11], v[162:163], v[10:11], v[114:115]
	v_cvt_pk_bf16_f32 v5, v6, v7
	v_pk_fma_f32 v[8:9], v[160:161], v[8:9], v[112:113]
	s_mov_b64 s[2:3], -1
	v_cvt_pk_bf16_f32 v6, v8, v9
	v_cvt_pk_bf16_f32 v7, v10, v11
	global_store_dwordx2 v[16:17], v[4:5], off offset:256
	global_store_dwordx2 v[12:13], v[6:7], off offset:256
	s_cbranch_vccnz .LBB0_218
	v_readlane_b32 s2, v254, 44
	v_readlane_b32 s3, v254, 45
	s_andn2_b64 vcc, exec, s[2:3]
	s_cbranch_vccnz .LBB0_217
	s_barrier
	s_branch .LBB0_217

.LBB0_687:
	s_or_b64 exec, exec, s[24:25]
	s_waitcnt lgkmcnt(0)
	s_barrier
	ds_write_b128 v180, v[128:131]
	ds_write_b128 v180, v[132:135] offset:64
	v_add_u32_e32 v198, v176, v183
	s_waitcnt lgkmcnt(2)
	v_cmp_eq_u32_e32 vcc, 0, v177
	ds_read_b128 v[130:133], v182
	ds_read_b128 v[174:177], v182 offset:1152
	ds_read2_b64 v[190:193], v185 offset1:8
	ds_write_b128 v180, v[136:139]
	ds_write_b128 v180, v[144:147] offset:64
	ds_read_b128 v[134:137], v182
	ds_read_b128 v[144:147], v182 offset:1152
	v_ashrrev_i32_e32 v199, 31, v198
	s_add_u32 s5, s20, s96
	v_lshl_add_u64 v[128:129], v[198:199], 1, s[22:23]
	s_mov_b64 s[18:19], 0x1ac00000
	s_waitcnt vmcnt(2)
	v_pk_add_f32 v[162:163], v[162:163], 1.0 op_sel_hi:[1,0]
	v_pk_add_f32 v[160:161], v[160:161], 1.0 op_sel_hi:[1,0]
	v_pk_add_f32 v[158:159], v[158:159], 1.0 op_sel_hi:[1,0]
	v_pk_add_f32 v[156:157], v[156:157], 1.0 op_sel_hi:[1,0]
	s_addc_u32 s20, s21, s97
	v_lshl_add_u64 v[128:129], v[128:129], 0, s[18:19]
	s_waitcnt lgkmcnt(4)
	v_sub_f32_e32 v131, v131, v190
	v_sub_f32_e32 v130, v130, v190
	v_pk_mul_f32 v[130:131], v[190:191], v[130:131] op_sel:[1,0]
	v_sub_f32_e32 v139, v175, v192
	v_sub_f32_e32 v138, v174, v192
	v_sub_f32_e32 v175, v177, v192
	v_sub_f32_e32 v174, v176, v192
	s_add_u32 s18, s5, s6
	v_sub_f32_e32 v133, v133, v190
	v_sub_f32_e32 v132, v132, v190
	v_pk_fma_f32 v[130:131], v[148:149], v[130:131], v[152:153]
	v_pk_mul_f32 v[174:175], v[192:193], v[174:175] op_sel:[1,0]
	s_addc_u32 s19, s20, s7
	v_pk_mul_f32 v[132:133], v[190:191], v[132:133] op_sel:[1,0]
	v_pk_fma_f32 v[194:195], v[150:151], v[174:175], v[154:155]
	v_cndmask_b32_e32 v175, v245, v131, vcc
	v_cndmask_b32_e32 v174, v245, v130, vcc
	v_lshlrev_b64 v[130:131], 2, v[198:199]
	v_pk_fma_f32 v[132:133], v[150:151], v[132:133], v[154:155]
	v_lshl_add_u64 v[198:199], s[18:19], 0, v[130:131]
	v_cndmask_b32_e32 v176, v245, v132, vcc
	v_add_co_u32_e64 v132, s[18:19], s71, v198
	v_cndmask_b32_e32 v177, v245, v133, vcc
	s_nop 0
	v_addc_co_u32_e64 v133, s[18:19], 0, v199, s[18:19]
	v_pk_mul_f32 v[138:139], v[192:193], v[138:139] op_sel:[1,0]
	s_add_i32 s18, s82, s2
	v_pk_fma_f32 v[138:139], v[148:149], v[138:139], v[152:153]
	s_ashr_i32 s19, s18, 31
	v_cndmask_b32_e32 v197, v245, v195, vcc
	v_cndmask_b32_e32 v196, v245, v194, vcc
	v_cndmask_b32_e32 v195, v245, v139, vcc
	v_cndmask_b32_e32 v194, v245, v138, vcc
	s_lshl_b64 s[18:19], s[18:19], 12
	global_store_dwordx4 v[198:199], v[174:177], off sc0 sc1 nt
	global_store_dwordx4 v[132:133], v[194:197], off sc0 sc1 nt
	s_waitcnt vmcnt(3)
	v_pk_fma_f32 v[132:133], v[158:159], v[176:177], v[142:143]
	v_pk_fma_f32 v[138:139], v[156:157], v[174:175], v[140:141]
	v_pk_fma_f32 v[176:177], v[156:157], v[194:195], v[140:141]
	v_lshl_add_u64 v[194:195], v[128:129], 0, s[18:19]
	v_pk_fma_f32 v[174:175], v[158:159], v[196:197], v[142:143]
	v_cvt_pk_bf16_f32 v138, v138, v139
	v_cvt_pk_bf16_f32 v139, v132, v133
	v_cvt_pk_bf16_f32 v132, v176, v177
	v_add_co_u32_e64 v196, s[18:19], s83, v194
	v_cvt_pk_bf16_f32 v133, v174, v175
	global_store_dwordx2 v[194:195], v[138:139], off
	ds_write_b128 v180, v[108:111]
	ds_write_b128 v180, v[116:119] offset:64
	ds_read_b128 v[108:111], v182
	ds_read_b128 v[116:119], v182 offset:1152
	ds_read2_b64 v[174:177], v185 offset0:16 offset1:24
	v_addc_co_u32_e64 v197, s[18:19], 0, v195, s[18:19]
	v_lshl_add_u64 v[200:201], v[198:199], 0, s[76:77]
	global_store_dwordx2 v[196:197], v[132:133], off
	s_waitcnt lgkmcnt(6)
	v_sub_f32_e32 v133, v135, v190
	v_sub_f32_e32 v132, v134, v190
	v_sub_f32_e32 v135, v137, v190
	v_sub_f32_e32 v134, v136, v190
	v_pk_mul_f32 v[134:135], v[190:191], v[134:135] op_sel:[1,0]
	v_pk_mul_f32 v[132:133], v[190:191], v[132:133] op_sel:[1,0]
	s_waitcnt lgkmcnt(5)
	v_sub_f32_e32 v137, v145, v192
	v_sub_f32_e32 v136, v144, v192
	v_sub_f32_e32 v139, v147, v192
	v_sub_f32_e32 v138, v146, v192
	v_pk_fma_f32 v[132:133], v[120:121], v[132:133], v[124:125]
	v_pk_fma_f32 v[134:135], v[122:123], v[134:135], v[126:127]
	v_pk_mul_f32 v[138:139], v[192:193], v[138:139] op_sel:[1,0]
	v_pk_mul_f32 v[136:137], v[192:193], v[136:137] op_sel:[1,0]
	v_pk_fma_f32 v[138:139], v[122:123], v[138:139], v[126:127]
	v_pk_fma_f32 v[136:137], v[120:121], v[136:137], v[124:125]
	v_cndmask_b32_e32 v135, v245, v135, vcc
	v_cndmask_b32_e32 v134, v245, v134, vcc
	v_cndmask_b32_e32 v133, v245, v133, vcc
	v_cndmask_b32_e32 v132, v245, v132, vcc
	v_cndmask_b32_e32 v139, v245, v139, vcc
	v_cndmask_b32_e32 v138, v245, v138, vcc
	v_cndmask_b32_e32 v137, v245, v137, vcc
	v_cndmask_b32_e32 v136, v245, v136, vcc
	global_store_dwordx4 v[198:199], v[132:135], off offset:512 sc0 sc1 nt
	global_store_dwordx4 v[200:201], v[136:139], off offset:512 sc0 sc1 nt
	s_waitcnt vmcnt(6)
	v_pk_fma_f32 v[134:135], v[162:163], v[134:135], v[114:115]
	v_pk_fma_f32 v[132:133], v[160:161], v[132:133], v[112:113]
	v_pk_fma_f32 v[138:139], v[162:163], v[138:139], v[114:115]
	v_pk_fma_f32 v[136:137], v[160:161], v[136:137], v[112:113]
	v_cvt_pk_bf16_f32 v132, v132, v133
	v_cvt_pk_bf16_f32 v133, v134, v135
	s_nop 0
	v_cvt_pk_bf16_f32 v134, v136, v137
	v_cvt_pk_bf16_f32 v135, v138, v139
	ds_write_b128 v180, v[100:103]
	ds_write_b128 v180, v[104:107] offset:64
	ds_read_b128 v[100:103], v182
	ds_read_b128 v[104:107], v182 offset:1152
	global_store_dwordx2 v[194:195], v[132:133], off offset:256
	global_store_dwordx2 v[196:197], v[134:135], off offset:256
	s_add_u32 s18, s5, s34
	s_addc_u32 s19, s20, s35
	v_lshl_add_u64 v[132:133], s[18:19], 0, v[130:131]
	v_add_co_u32_e64 v136, s[18:19], s71, v132
	s_waitcnt lgkmcnt(4)
	v_sub_f32_e32 v109, v109, v174
	v_sub_f32_e32 v108, v108, v174
	v_sub_f32_e32 v111, v111, v174
	v_sub_f32_e32 v110, v110, v174
	v_sub_f32_e32 v117, v117, v176
	v_sub_f32_e32 v116, v116, v176
	v_sub_f32_e32 v119, v119, v176
	v_sub_f32_e32 v118, v118, v176
	v_addc_co_u32_e64 v137, s[18:19], 0, v133, s[18:19]
	v_pk_mul_f32 v[110:111], v[174:175], v[110:111] op_sel:[1,0]
	v_pk_mul_f32 v[108:109], v[174:175], v[108:109] op_sel:[1,0]
	v_pk_mul_f32 v[118:119], v[176:177], v[118:119] op_sel:[1,0]
	v_pk_mul_f32 v[116:117], v[176:177], v[116:117] op_sel:[1,0]
	v_readlane_b32 s18, v254, 56
	v_pk_fma_f32 v[108:109], v[148:149], v[108:109], v[152:153]
	v_pk_fma_f32 v[110:111], v[150:151], v[110:111], v[154:155]
	v_pk_fma_f32 v[116:117], v[148:149], v[116:117], v[152:153]
	v_pk_fma_f32 v[118:119], v[150:151], v[118:119], v[154:155]
	v_readlane_b32 s19, v254, 57
	s_add_i32 s18, s82, s18
	v_cndmask_b32_e32 v111, v245, v111, vcc
	v_cndmask_b32_e32 v110, v245, v110, vcc
	v_cndmask_b32_e32 v109, v245, v109, vcc
	v_cndmask_b32_e32 v108, v245, v108, vcc
	v_cndmask_b32_e32 v119, v245, v119, vcc
	v_cndmask_b32_e32 v118, v245, v118, vcc
	v_cndmask_b32_e32 v117, v245, v117, vcc
	v_cndmask_b32_e32 v116, v245, v116, vcc
	s_ashr_i32 s19, s18, 31
	global_store_dwordx4 v[132:133], v[108:111], off sc0 sc1 nt
	global_store_dwordx4 v[136:137], v[116:119], off sc0 sc1 nt
	s_lshl_b64 s[18:19], s[18:19], 12
	v_pk_fma_f32 v[108:109], v[156:157], v[108:109], v[140:141]
	v_pk_fma_f32 v[118:119], v[158:159], v[118:119], v[142:143]
	v_pk_fma_f32 v[116:117], v[156:157], v[116:117], v[140:141]
	v_pk_fma_f32 v[110:111], v[158:159], v[110:111], v[142:143]
	v_cvt_pk_bf16_f32 v108, v108, v109
	v_lshl_add_u64 v[134:135], v[132:133], 0, s[76:77]
	v_cvt_pk_bf16_f32 v109, v110, v111
	v_cvt_pk_bf16_f32 v116, v116, v117
	v_cvt_pk_bf16_f32 v117, v118, v119
	v_lshl_add_u64 v[118:119], v[128:129], 0, s[18:19]
	global_store_dwordx2 v[118:119], v[108:109], off
	ds_write_b128 v180, v[92:95]
	ds_write_b128 v180, v[96:99] offset:64
	ds_read_b128 v[92:95], v182
	ds_read_b128 v[96:99], v182 offset:1152
	ds_read2_b64 v[108:111], v185 offset0:32 offset1:40
	v_add_co_u32_e64 v136, s[18:19], s83, v118
	s_nop 1
	v_addc_co_u32_e64 v137, s[18:19], 0, v119, s[18:19]
	global_store_dwordx2 v[136:137], v[116:117], off
	s_waitcnt lgkmcnt(6)
	v_sub_f32_e32 v101, v101, v174
	v_sub_f32_e32 v100, v100, v174
	v_sub_f32_e32 v103, v103, v174
	v_sub_f32_e32 v102, v102, v174
	v_pk_mul_f32 v[102:103], v[174:175], v[102:103] op_sel:[1,0]
	v_pk_mul_f32 v[100:101], v[174:175], v[100:101] op_sel:[1,0]
	s_waitcnt lgkmcnt(5)
	v_sub_f32_e32 v105, v105, v176
	v_sub_f32_e32 v104, v104, v176
	v_sub_f32_e32 v107, v107, v176
	v_sub_f32_e32 v106, v106, v176
	v_pk_fma_f32 v[100:101], v[120:121], v[100:101], v[124:125]
	v_pk_fma_f32 v[102:103], v[122:123], v[102:103], v[126:127]
	v_pk_mul_f32 v[106:107], v[176:177], v[106:107] op_sel:[1,0]
	v_pk_mul_f32 v[104:105], v[176:177], v[104:105] op_sel:[1,0]
	v_pk_fma_f32 v[106:107], v[122:123], v[106:107], v[126:127]
	v_pk_fma_f32 v[104:105], v[120:121], v[104:105], v[124:125]
	v_cndmask_b32_e32 v103, v245, v103, vcc
	v_cndmask_b32_e32 v102, v245, v102, vcc
	v_cndmask_b32_e32 v101, v245, v101, vcc
	v_cndmask_b32_e32 v100, v245, v100, vcc
	v_cndmask_b32_e32 v107, v245, v107, vcc
	v_cndmask_b32_e32 v106, v245, v106, vcc
	v_cndmask_b32_e32 v105, v245, v105, vcc
	v_cndmask_b32_e32 v104, v245, v104, vcc
	global_store_dwordx4 v[132:133], v[100:103], off offset:512 sc0 sc1 nt
	global_store_dwordx4 v[134:135], v[104:107], off offset:512 sc0 sc1 nt
	s_nop 0
	v_pk_fma_f32 v[100:101], v[160:161], v[100:101], v[112:113]
	v_pk_fma_f32 v[102:103], v[162:163], v[102:103], v[114:115]
	v_cvt_pk_bf16_f32 v100, v100, v101
	v_pk_fma_f32 v[106:107], v[162:163], v[106:107], v[114:115]
	v_cvt_pk_bf16_f32 v101, v102, v103
	v_pk_fma_f32 v[104:105], v[160:161], v[104:105], v[112:113]
	s_nop 0
	v_cvt_pk_bf16_f32 v102, v104, v105
	v_cvt_pk_bf16_f32 v103, v106, v107
	global_store_dwordx2 v[118:119], v[100:101], off offset:256
	global_store_dwordx2 v[136:137], v[102:103], off offset:256
	ds_write_b128 v180, v[84:87]
	ds_write_b128 v180, v[88:91] offset:64
	ds_read_b128 v[84:87], v182
	ds_read_b128 v[88:91], v182 offset:1152
	s_add_u32 s18, s5, s40
	s_addc_u32 s19, s20, s41
	v_lshl_add_u64 v[100:101], s[18:19], 0, v[130:131]
	v_add_co_u32_e64 v104, s[18:19], s71, v100
	s_waitcnt lgkmcnt(4)
	v_sub_f32_e32 v93, v93, v108
	v_sub_f32_e32 v92, v92, v108
	v_sub_f32_e32 v95, v95, v108
	v_sub_f32_e32 v94, v94, v108
	v_sub_f32_e32 v97, v97, v110
	v_sub_f32_e32 v96, v96, v110
	v_sub_f32_e32 v99, v99, v110
	v_sub_f32_e32 v98, v98, v110
	v_addc_co_u32_e64 v105, s[18:19], 0, v101, s[18:19]
	v_pk_mul_f32 v[94:95], v[108:109], v[94:95] op_sel:[1,0]
	v_pk_mul_f32 v[92:93], v[108:109], v[92:93] op_sel:[1,0]
	v_pk_mul_f32 v[98:99], v[110:111], v[98:99] op_sel:[1,0]
	v_pk_mul_f32 v[96:97], v[110:111], v[96:97] op_sel:[1,0]
	v_readlane_b32 s18, v254, 60
	v_pk_fma_f32 v[92:93], v[148:149], v[92:93], v[152:153]
	v_pk_fma_f32 v[94:95], v[150:151], v[94:95], v[154:155]
	v_pk_fma_f32 v[96:97], v[148:149], v[96:97], v[152:153]
	v_pk_fma_f32 v[98:99], v[150:151], v[98:99], v[154:155]
	v_readlane_b32 s19, v254, 61
	s_add_i32 s18, s82, s18
	v_cndmask_b32_e32 v95, v245, v95, vcc
	v_cndmask_b32_e32 v94, v245, v94, vcc
	v_cndmask_b32_e32 v93, v245, v93, vcc
	v_cndmask_b32_e32 v92, v245, v92, vcc
	v_cndmask_b32_e32 v99, v245, v99, vcc
	v_cndmask_b32_e32 v98, v245, v98, vcc
	v_cndmask_b32_e32 v97, v245, v97, vcc
	v_cndmask_b32_e32 v96, v245, v96, vcc
	s_ashr_i32 s19, s18, 31
	global_store_dwordx4 v[100:101], v[92:95], off sc0 sc1 nt
	global_store_dwordx4 v[104:105], v[96:99], off sc0 sc1 nt
	s_lshl_b64 s[18:19], s[18:19], 12
	v_pk_fma_f32 v[92:93], v[156:157], v[92:93], v[140:141]
	v_pk_fma_f32 v[98:99], v[158:159], v[98:99], v[142:143]
	v_pk_fma_f32 v[96:97], v[156:157], v[96:97], v[140:141]
	v_pk_fma_f32 v[94:95], v[158:159], v[94:95], v[142:143]
	v_cvt_pk_bf16_f32 v92, v92, v93
	v_lshl_add_u64 v[102:103], v[100:101], 0, s[76:77]
	v_cvt_pk_bf16_f32 v93, v94, v95
	v_cvt_pk_bf16_f32 v96, v96, v97
	v_cvt_pk_bf16_f32 v97, v98, v99
	v_lshl_add_u64 v[98:99], v[128:129], 0, s[18:19]
	global_store_dwordx2 v[98:99], v[92:93], off
	ds_write_b128 v180, v[76:79]
	ds_write_b128 v180, v[80:83] offset:64
	ds_read_b128 v[76:79], v182
	ds_read_b128 v[80:83], v182 offset:1152
	ds_read2_b64 v[92:95], v185 offset0:48 offset1:56
	v_add_co_u32_e64 v104, s[18:19], s83, v98
	s_nop 1
	v_addc_co_u32_e64 v105, s[18:19], 0, v99, s[18:19]
	global_store_dwordx2 v[104:105], v[96:97], off
	s_waitcnt lgkmcnt(6)
	v_sub_f32_e32 v85, v85, v108
	v_sub_f32_e32 v84, v84, v108
	v_sub_f32_e32 v87, v87, v108
	v_sub_f32_e32 v86, v86, v108
	v_pk_mul_f32 v[86:87], v[108:109], v[86:87] op_sel:[1,0]
	v_pk_mul_f32 v[84:85], v[108:109], v[84:85] op_sel:[1,0]
	s_waitcnt lgkmcnt(5)
	v_sub_f32_e32 v89, v89, v110
	v_sub_f32_e32 v88, v88, v110
	v_sub_f32_e32 v91, v91, v110
	v_sub_f32_e32 v90, v90, v110
	v_pk_fma_f32 v[84:85], v[120:121], v[84:85], v[124:125]
	v_pk_fma_f32 v[86:87], v[122:123], v[86:87], v[126:127]
	v_pk_mul_f32 v[90:91], v[110:111], v[90:91] op_sel:[1,0]
	v_pk_mul_f32 v[88:89], v[110:111], v[88:89] op_sel:[1,0]
	v_pk_fma_f32 v[90:91], v[122:123], v[90:91], v[126:127]
	v_pk_fma_f32 v[88:89], v[120:121], v[88:89], v[124:125]
	v_cndmask_b32_e32 v87, v245, v87, vcc
	v_cndmask_b32_e32 v86, v245, v86, vcc
	v_cndmask_b32_e32 v85, v245, v85, vcc
	v_cndmask_b32_e32 v84, v245, v84, vcc
	v_cndmask_b32_e32 v91, v245, v91, vcc
	v_cndmask_b32_e32 v90, v245, v90, vcc
	v_cndmask_b32_e32 v89, v245, v89, vcc
	v_cndmask_b32_e32 v88, v245, v88, vcc
	global_store_dwordx4 v[100:101], v[84:87], off offset:512 sc0 sc1 nt
	global_store_dwordx4 v[102:103], v[88:91], off offset:512 sc0 sc1 nt
	s_nop 0
	v_pk_fma_f32 v[86:87], v[162:163], v[86:87], v[114:115]
	v_pk_fma_f32 v[84:85], v[160:161], v[84:85], v[112:113]
	v_pk_fma_f32 v[90:91], v[162:163], v[90:91], v[114:115]
	v_pk_fma_f32 v[88:89], v[160:161], v[88:89], v[112:113]
	v_cvt_pk_bf16_f32 v84, v84, v85
	v_cvt_pk_bf16_f32 v85, v86, v87
	s_nop 0
	v_cvt_pk_bf16_f32 v86, v88, v89
	v_cvt_pk_bf16_f32 v87, v90, v91
	ds_write_b128 v180, v[68:71]
	ds_write_b128 v180, v[72:75] offset:64
	ds_read_b128 v[68:71], v182
	ds_read_b128 v[72:75], v182 offset:1152
	global_store_dwordx2 v[98:99], v[84:85], off offset:256
	global_store_dwordx2 v[104:105], v[86:87], off offset:256
	s_add_u32 s18, s5, s46
	s_addc_u32 s19, s20, s47
	v_lshl_add_u64 v[84:85], s[18:19], 0, v[130:131]
	v_add_co_u32_e64 v88, s[18:19], s71, v84
	s_waitcnt lgkmcnt(4)
	v_sub_f32_e32 v77, v77, v92
	v_sub_f32_e32 v76, v76, v92
	v_sub_f32_e32 v79, v79, v92
	v_sub_f32_e32 v78, v78, v92
	v_sub_f32_e32 v81, v81, v94
	v_sub_f32_e32 v80, v80, v94
	v_sub_f32_e32 v83, v83, v94
	v_sub_f32_e32 v82, v82, v94
	v_addc_co_u32_e64 v89, s[18:19], 0, v85, s[18:19]
	v_pk_mul_f32 v[78:79], v[92:93], v[78:79] op_sel:[1,0]
	v_pk_mul_f32 v[76:77], v[92:93], v[76:77] op_sel:[1,0]
	v_pk_mul_f32 v[82:83], v[94:95], v[82:83] op_sel:[1,0]
	v_pk_mul_f32 v[80:81], v[94:95], v[80:81] op_sel:[1,0]
	v_readlane_b32 s18, v255, 0
	v_pk_fma_f32 v[76:77], v[148:149], v[76:77], v[152:153]
	v_pk_fma_f32 v[78:79], v[150:151], v[78:79], v[154:155]
	v_pk_fma_f32 v[80:81], v[148:149], v[80:81], v[152:153]
	v_pk_fma_f32 v[82:83], v[150:151], v[82:83], v[154:155]
	v_readlane_b32 s19, v255, 1
	s_add_i32 s18, s82, s18
	v_cndmask_b32_e32 v79, v245, v79, vcc
	v_cndmask_b32_e32 v78, v245, v78, vcc
	v_cndmask_b32_e32 v77, v245, v77, vcc
	v_cndmask_b32_e32 v76, v245, v76, vcc
	v_cndmask_b32_e32 v83, v245, v83, vcc
	v_cndmask_b32_e32 v82, v245, v82, vcc
	v_cndmask_b32_e32 v81, v245, v81, vcc
	v_cndmask_b32_e32 v80, v245, v80, vcc
	s_ashr_i32 s19, s18, 31
	global_store_dwordx4 v[84:85], v[76:79], off sc0 sc1 nt
	global_store_dwordx4 v[88:89], v[80:83], off sc0 sc1 nt
	s_lshl_b64 s[18:19], s[18:19], 12
	v_pk_fma_f32 v[76:77], v[156:157], v[76:77], v[140:141]
	v_pk_fma_f32 v[82:83], v[158:159], v[82:83], v[142:143]
	v_pk_fma_f32 v[80:81], v[156:157], v[80:81], v[140:141]
	v_pk_fma_f32 v[78:79], v[158:159], v[78:79], v[142:143]
	v_cvt_pk_bf16_f32 v76, v76, v77
	v_lshl_add_u64 v[86:87], v[84:85], 0, s[76:77]
	v_cvt_pk_bf16_f32 v77, v78, v79
	v_cvt_pk_bf16_f32 v80, v80, v81
	v_cvt_pk_bf16_f32 v81, v82, v83
	v_lshl_add_u64 v[82:83], v[128:129], 0, s[18:19]
	global_store_dwordx2 v[82:83], v[76:77], off
	ds_write_b128 v180, v[60:63]
	ds_write_b128 v180, v[64:67] offset:64
	ds_read_b128 v[60:63], v182
	ds_read_b128 v[64:67], v182 offset:1152
	ds_read2_b64 v[76:79], v185 offset0:128 offset1:136
	v_add_co_u32_e64 v88, s[18:19], s83, v82
	s_nop 1
	v_addc_co_u32_e64 v89, s[18:19], 0, v83, s[18:19]
	global_store_dwordx2 v[88:89], v[80:81], off
	s_waitcnt lgkmcnt(6)
	v_sub_f32_e32 v69, v69, v92
	v_sub_f32_e32 v68, v68, v92
	v_sub_f32_e32 v71, v71, v92
	v_sub_f32_e32 v70, v70, v92
	v_pk_mul_f32 v[70:71], v[92:93], v[70:71] op_sel:[1,0]
	v_pk_mul_f32 v[68:69], v[92:93], v[68:69] op_sel:[1,0]
	s_waitcnt lgkmcnt(5)
	v_sub_f32_e32 v73, v73, v94
	v_sub_f32_e32 v72, v72, v94
	v_sub_f32_e32 v75, v75, v94
	v_sub_f32_e32 v74, v74, v94
	v_pk_fma_f32 v[68:69], v[120:121], v[68:69], v[124:125]
	v_pk_fma_f32 v[70:71], v[122:123], v[70:71], v[126:127]
	v_pk_mul_f32 v[74:75], v[94:95], v[74:75] op_sel:[1,0]
	v_pk_mul_f32 v[72:73], v[94:95], v[72:73] op_sel:[1,0]
	v_pk_fma_f32 v[74:75], v[122:123], v[74:75], v[126:127]
	v_pk_fma_f32 v[72:73], v[120:121], v[72:73], v[124:125]
	v_cndmask_b32_e32 v71, v245, v71, vcc
	v_cndmask_b32_e32 v70, v245, v70, vcc
	v_cndmask_b32_e32 v69, v245, v69, vcc
	v_cndmask_b32_e32 v68, v245, v68, vcc
	v_cndmask_b32_e32 v75, v245, v75, vcc
	v_cndmask_b32_e32 v74, v245, v74, vcc
	v_cndmask_b32_e32 v73, v245, v73, vcc
	v_cndmask_b32_e32 v72, v245, v72, vcc
	global_store_dwordx4 v[84:85], v[68:71], off offset:512 sc0 sc1 nt
	global_store_dwordx4 v[86:87], v[72:75], off offset:512 sc0 sc1 nt
	s_nop 0
	v_pk_fma_f32 v[68:69], v[160:161], v[68:69], v[112:113]
	v_pk_fma_f32 v[70:71], v[162:163], v[70:71], v[114:115]
	v_cvt_pk_bf16_f32 v68, v68, v69
	v_pk_fma_f32 v[74:75], v[162:163], v[74:75], v[114:115]
	v_cvt_pk_bf16_f32 v69, v70, v71
	v_pk_fma_f32 v[72:73], v[160:161], v[72:73], v[112:113]
	s_nop 0
	v_cvt_pk_bf16_f32 v70, v72, v73
	v_cvt_pk_bf16_f32 v71, v74, v75
	global_store_dwordx2 v[82:83], v[68:69], off offset:256
	global_store_dwordx2 v[88:89], v[70:71], off offset:256
	ds_write_b128 v180, v[52:55]
	ds_write_b128 v180, v[56:59] offset:64
	ds_read_b128 v[52:55], v182
	ds_read_b128 v[56:59], v182 offset:1152
	s_add_u32 s18, s5, s52
	s_addc_u32 s19, s20, s53
	v_lshl_add_u64 v[68:69], s[18:19], 0, v[130:131]
	v_add_co_u32_e64 v72, s[18:19], s71, v68
	s_waitcnt lgkmcnt(4)
	v_sub_f32_e32 v61, v61, v76
	v_sub_f32_e32 v60, v60, v76
	v_sub_f32_e32 v63, v63, v76
	v_sub_f32_e32 v62, v62, v76
	v_sub_f32_e32 v65, v65, v78
	v_sub_f32_e32 v64, v64, v78
	v_sub_f32_e32 v67, v67, v78
	v_sub_f32_e32 v66, v66, v78
	v_addc_co_u32_e64 v73, s[18:19], 0, v69, s[18:19]
	v_pk_mul_f32 v[62:63], v[76:77], v[62:63] op_sel:[1,0]
	v_pk_mul_f32 v[60:61], v[76:77], v[60:61] op_sel:[1,0]
	v_pk_mul_f32 v[66:67], v[78:79], v[66:67] op_sel:[1,0]
	v_pk_mul_f32 v[64:65], v[78:79], v[64:65] op_sel:[1,0]
	v_readlane_b32 s18, v255, 4
	v_pk_fma_f32 v[60:61], v[148:149], v[60:61], v[152:153]
	v_pk_fma_f32 v[62:63], v[150:151], v[62:63], v[154:155]
	v_pk_fma_f32 v[64:65], v[148:149], v[64:65], v[152:153]
	v_pk_fma_f32 v[66:67], v[150:151], v[66:67], v[154:155]
	v_readlane_b32 s19, v255, 5
	s_add_i32 s18, s82, s18
	v_cndmask_b32_e32 v63, v245, v63, vcc
	v_cndmask_b32_e32 v62, v245, v62, vcc
	v_cndmask_b32_e32 v61, v245, v61, vcc
	v_cndmask_b32_e32 v60, v245, v60, vcc
	v_cndmask_b32_e32 v67, v245, v67, vcc
	v_cndmask_b32_e32 v66, v245, v66, vcc
	v_cndmask_b32_e32 v65, v245, v65, vcc
	v_cndmask_b32_e32 v64, v245, v64, vcc
	s_ashr_i32 s19, s18, 31
	global_store_dwordx4 v[68:69], v[60:63], off sc0 sc1 nt
	global_store_dwordx4 v[72:73], v[64:67], off sc0 sc1 nt
	s_lshl_b64 s[18:19], s[18:19], 12
	v_pk_fma_f32 v[60:61], v[156:157], v[60:61], v[140:141]
	v_pk_fma_f32 v[66:67], v[158:159], v[66:67], v[142:143]
	v_pk_fma_f32 v[64:65], v[156:157], v[64:65], v[140:141]
	v_pk_fma_f32 v[62:63], v[158:159], v[62:63], v[142:143]
	v_cvt_pk_bf16_f32 v60, v60, v61
	v_lshl_add_u64 v[70:71], v[68:69], 0, s[76:77]
	v_cvt_pk_bf16_f32 v61, v62, v63
	v_cvt_pk_bf16_f32 v64, v64, v65
	v_cvt_pk_bf16_f32 v65, v66, v67
	v_lshl_add_u64 v[66:67], v[128:129], 0, s[18:19]
	global_store_dwordx2 v[66:67], v[60:61], off
	ds_write_b128 v180, v[44:47]
	ds_write_b128 v180, v[48:51] offset:64
	ds_read_b128 v[44:47], v182
	ds_read_b128 v[48:51], v182 offset:1152
	ds_read2_b64 v[60:63], v185 offset0:144 offset1:152
	v_add_co_u32_e64 v72, s[18:19], s83, v66
	s_nop 1
	v_addc_co_u32_e64 v73, s[18:19], 0, v67, s[18:19]
	global_store_dwordx2 v[72:73], v[64:65], off
	s_waitcnt lgkmcnt(6)
	v_sub_f32_e32 v53, v53, v76
	v_sub_f32_e32 v52, v52, v76
	v_sub_f32_e32 v55, v55, v76
	v_sub_f32_e32 v54, v54, v76
	v_pk_mul_f32 v[54:55], v[76:77], v[54:55] op_sel:[1,0]
	v_pk_mul_f32 v[52:53], v[76:77], v[52:53] op_sel:[1,0]
	s_waitcnt lgkmcnt(5)
	v_sub_f32_e32 v57, v57, v78
	v_sub_f32_e32 v56, v56, v78
	v_sub_f32_e32 v59, v59, v78
	v_sub_f32_e32 v58, v58, v78
	v_pk_fma_f32 v[52:53], v[120:121], v[52:53], v[124:125]
	v_pk_fma_f32 v[54:55], v[122:123], v[54:55], v[126:127]
	v_pk_mul_f32 v[58:59], v[78:79], v[58:59] op_sel:[1,0]
	v_pk_mul_f32 v[56:57], v[78:79], v[56:57] op_sel:[1,0]
	v_pk_fma_f32 v[58:59], v[122:123], v[58:59], v[126:127]
	v_pk_fma_f32 v[56:57], v[120:121], v[56:57], v[124:125]
	v_cndmask_b32_e32 v55, v245, v55, vcc
	v_cndmask_b32_e32 v54, v245, v54, vcc
	v_cndmask_b32_e32 v53, v245, v53, vcc
	v_cndmask_b32_e32 v52, v245, v52, vcc
	v_cndmask_b32_e32 v59, v245, v59, vcc
	v_cndmask_b32_e32 v58, v245, v58, vcc
	v_cndmask_b32_e32 v57, v245, v57, vcc
	v_cndmask_b32_e32 v56, v245, v56, vcc
	global_store_dwordx4 v[68:69], v[52:55], off offset:512 sc0 sc1 nt
	global_store_dwordx4 v[70:71], v[56:59], off offset:512 sc0 sc1 nt
	s_nop 0
	v_pk_fma_f32 v[54:55], v[162:163], v[54:55], v[114:115]
	v_pk_fma_f32 v[52:53], v[160:161], v[52:53], v[112:113]
	v_pk_fma_f32 v[58:59], v[162:163], v[58:59], v[114:115]
	v_pk_fma_f32 v[56:57], v[160:161], v[56:57], v[112:113]
	v_cvt_pk_bf16_f32 v52, v52, v53
	v_cvt_pk_bf16_f32 v53, v54, v55
	s_nop 0
	v_cvt_pk_bf16_f32 v54, v56, v57
	v_cvt_pk_bf16_f32 v55, v58, v59
	ds_write_b128 v180, v[36:39]
	ds_write_b128 v180, v[40:43] offset:64
	ds_read_b128 v[36:39], v182
	ds_read_b128 v[40:43], v182 offset:1152
	global_store_dwordx2 v[66:67], v[52:53], off offset:256
	global_store_dwordx2 v[72:73], v[54:55], off offset:256
	s_add_u32 s18, s5, s58
	s_addc_u32 s19, s20, s59
	v_lshl_add_u64 v[52:53], s[18:19], 0, v[130:131]
	v_add_co_u32_e64 v56, s[18:19], s71, v52
	s_waitcnt lgkmcnt(4)
	v_sub_f32_e32 v45, v45, v60
	v_sub_f32_e32 v44, v44, v60
	v_sub_f32_e32 v47, v47, v60
	v_sub_f32_e32 v46, v46, v60
	v_sub_f32_e32 v49, v49, v62
	v_sub_f32_e32 v48, v48, v62
	v_sub_f32_e32 v51, v51, v62
	v_sub_f32_e32 v50, v50, v62
	v_addc_co_u32_e64 v57, s[18:19], 0, v53, s[18:19]
	v_pk_mul_f32 v[46:47], v[60:61], v[46:47] op_sel:[1,0]
	v_pk_mul_f32 v[44:45], v[60:61], v[44:45] op_sel:[1,0]
	v_pk_mul_f32 v[50:51], v[62:63], v[50:51] op_sel:[1,0]
	v_pk_mul_f32 v[48:49], v[62:63], v[48:49] op_sel:[1,0]
	v_readlane_b32 s18, v255, 10
	v_pk_fma_f32 v[44:45], v[148:149], v[44:45], v[152:153]
	v_pk_fma_f32 v[46:47], v[150:151], v[46:47], v[154:155]
	v_pk_fma_f32 v[48:49], v[148:149], v[48:49], v[152:153]
	v_pk_fma_f32 v[50:51], v[150:151], v[50:51], v[154:155]
	v_readlane_b32 s19, v255, 11
	s_add_i32 s18, s82, s18
	v_cndmask_b32_e32 v47, v245, v47, vcc
	v_cndmask_b32_e32 v46, v245, v46, vcc
	v_cndmask_b32_e32 v45, v245, v45, vcc
	v_cndmask_b32_e32 v44, v245, v44, vcc
	v_cndmask_b32_e32 v51, v245, v51, vcc
	v_cndmask_b32_e32 v50, v245, v50, vcc
	v_cndmask_b32_e32 v49, v245, v49, vcc
	v_cndmask_b32_e32 v48, v245, v48, vcc
	s_ashr_i32 s19, s18, 31
	global_store_dwordx4 v[52:53], v[44:47], off sc0 sc1 nt
	global_store_dwordx4 v[56:57], v[48:51], off sc0 sc1 nt
	s_lshl_b64 s[18:19], s[18:19], 12
	v_pk_fma_f32 v[44:45], v[156:157], v[44:45], v[140:141]
	v_pk_fma_f32 v[50:51], v[158:159], v[50:51], v[142:143]
	v_pk_fma_f32 v[48:49], v[156:157], v[48:49], v[140:141]
	v_pk_fma_f32 v[46:47], v[158:159], v[46:47], v[142:143]
	v_cvt_pk_bf16_f32 v44, v44, v45
	v_lshl_add_u64 v[54:55], v[52:53], 0, s[76:77]
	v_cvt_pk_bf16_f32 v45, v46, v47
	v_cvt_pk_bf16_f32 v48, v48, v49
	v_cvt_pk_bf16_f32 v49, v50, v51
	v_lshl_add_u64 v[50:51], v[128:129], 0, s[18:19]
	global_store_dwordx2 v[50:51], v[44:45], off
	ds_write_b128 v180, v[28:31]
	ds_write_b128 v180, v[32:35] offset:64
	ds_read_b128 v[28:31], v182
	ds_read_b128 v[32:35], v182 offset:1152
	ds_read2_b64 v[44:47], v185 offset0:160 offset1:168
	v_add_co_u32_e64 v56, s[18:19], s83, v50
	s_nop 1
	v_addc_co_u32_e64 v57, s[18:19], 0, v51, s[18:19]
	global_store_dwordx2 v[56:57], v[48:49], off
	s_waitcnt lgkmcnt(6)
	v_sub_f32_e32 v37, v37, v60
	v_sub_f32_e32 v36, v36, v60
	v_sub_f32_e32 v39, v39, v60
	v_sub_f32_e32 v38, v38, v60
	v_pk_mul_f32 v[38:39], v[60:61], v[38:39] op_sel:[1,0]
	v_pk_mul_f32 v[36:37], v[60:61], v[36:37] op_sel:[1,0]
	s_waitcnt lgkmcnt(5)
	v_sub_f32_e32 v41, v41, v62
	v_sub_f32_e32 v40, v40, v62
	v_sub_f32_e32 v43, v43, v62
	v_sub_f32_e32 v42, v42, v62
	v_pk_fma_f32 v[36:37], v[120:121], v[36:37], v[124:125]
	v_pk_fma_f32 v[38:39], v[122:123], v[38:39], v[126:127]
	v_pk_mul_f32 v[42:43], v[62:63], v[42:43] op_sel:[1,0]
	v_pk_mul_f32 v[40:41], v[62:63], v[40:41] op_sel:[1,0]
	v_pk_fma_f32 v[42:43], v[122:123], v[42:43], v[126:127]
	v_pk_fma_f32 v[40:41], v[120:121], v[40:41], v[124:125]
	v_cndmask_b32_e32 v39, v245, v39, vcc
	v_cndmask_b32_e32 v38, v245, v38, vcc
	v_cndmask_b32_e32 v37, v245, v37, vcc
	v_cndmask_b32_e32 v36, v245, v36, vcc
	v_cndmask_b32_e32 v43, v245, v43, vcc
	v_cndmask_b32_e32 v42, v245, v42, vcc
	v_cndmask_b32_e32 v41, v245, v41, vcc
	v_cndmask_b32_e32 v40, v245, v40, vcc
	global_store_dwordx4 v[52:53], v[36:39], off offset:512 sc0 sc1 nt
	global_store_dwordx4 v[54:55], v[40:43], off offset:512 sc0 sc1 nt
	s_nop 0
	v_pk_fma_f32 v[36:37], v[160:161], v[36:37], v[112:113]
	v_pk_fma_f32 v[38:39], v[162:163], v[38:39], v[114:115]
	v_cvt_pk_bf16_f32 v36, v36, v37
	v_pk_fma_f32 v[42:43], v[162:163], v[42:43], v[114:115]
	v_cvt_pk_bf16_f32 v37, v38, v39
	v_pk_fma_f32 v[40:41], v[160:161], v[40:41], v[112:113]
	s_nop 0
	v_cvt_pk_bf16_f32 v38, v40, v41
	v_cvt_pk_bf16_f32 v39, v42, v43
	global_store_dwordx2 v[50:51], v[36:37], off offset:256
	global_store_dwordx2 v[56:57], v[38:39], off offset:256
	ds_write_b128 v180, v[20:23]
	ds_write_b128 v180, v[24:27] offset:64
	ds_read_b128 v[20:23], v182
	ds_read_b128 v[24:27], v182 offset:1152
	s_add_u32 s18, s5, s64
	s_addc_u32 s19, s20, s65
	v_lshl_add_u64 v[36:37], s[18:19], 0, v[130:131]
	s_waitcnt lgkmcnt(4)
	v_sub_f32_e32 v29, v29, v44
	v_sub_f32_e32 v28, v28, v44
	v_sub_f32_e32 v31, v31, v44
	v_sub_f32_e32 v30, v30, v44
	v_sub_f32_e32 v33, v33, v46
	v_sub_f32_e32 v32, v32, v46
	v_sub_f32_e32 v35, v35, v46
	v_sub_f32_e32 v34, v34, v46
	v_add_co_u32_e64 v40, s[18:19], s71, v36
	v_pk_mul_f32 v[30:31], v[44:45], v[30:31] op_sel:[1,0]
	v_pk_mul_f32 v[28:29], v[44:45], v[28:29] op_sel:[1,0]
	v_pk_mul_f32 v[34:35], v[46:47], v[34:35] op_sel:[1,0]
	v_pk_mul_f32 v[32:33], v[46:47], v[32:33] op_sel:[1,0]
	v_addc_co_u32_e64 v41, s[18:19], 0, v37, s[18:19]
	v_pk_fma_f32 v[28:29], v[148:149], v[28:29], v[152:153]
	v_pk_fma_f32 v[30:31], v[150:151], v[30:31], v[154:155]
	v_pk_fma_f32 v[32:33], v[148:149], v[32:33], v[152:153]
	v_pk_fma_f32 v[34:35], v[150:151], v[34:35], v[154:155]
	s_add_i32 s18, s82, s62
	v_cndmask_b32_e32 v31, v245, v31, vcc
	v_cndmask_b32_e32 v30, v245, v30, vcc
	v_cndmask_b32_e32 v29, v245, v29, vcc
	v_cndmask_b32_e32 v28, v245, v28, vcc
	v_cndmask_b32_e32 v35, v245, v35, vcc
	v_cndmask_b32_e32 v34, v245, v34, vcc
	v_cndmask_b32_e32 v33, v245, v33, vcc
	v_cndmask_b32_e32 v32, v245, v32, vcc
	s_ashr_i32 s19, s18, 31
	global_store_dwordx4 v[36:37], v[28:31], off sc0 sc1 nt
	global_store_dwordx4 v[40:41], v[32:35], off sc0 sc1 nt
	s_lshl_b64 s[18:19], s[18:19], 12
	v_pk_fma_f32 v[28:29], v[156:157], v[28:29], v[140:141]
	v_pk_fma_f32 v[34:35], v[158:159], v[34:35], v[142:143]
	v_pk_fma_f32 v[32:33], v[156:157], v[32:33], v[140:141]
	v_pk_fma_f32 v[30:31], v[158:159], v[30:31], v[142:143]
	v_cvt_pk_bf16_f32 v28, v28, v29
	v_lshl_add_u64 v[38:39], v[36:37], 0, s[76:77]
	v_cvt_pk_bf16_f32 v29, v30, v31
	v_cvt_pk_bf16_f32 v32, v32, v33
	v_cvt_pk_bf16_f32 v33, v34, v35
	v_lshl_add_u64 v[34:35], v[128:129], 0, s[18:19]
	global_store_dwordx2 v[34:35], v[28:29], off
	ds_write_b128 v180, v[12:15]
	ds_write_b128 v180, v[16:19] offset:64
	ds_read_b128 v[12:15], v182
	ds_read_b128 v[16:19], v182 offset:1152
	ds_read2_b64 v[28:31], v185 offset0:176 offset1:184
	v_add_co_u32_e64 v40, s[18:19], s83, v34
	s_nop 1
	v_addc_co_u32_e64 v41, s[18:19], 0, v35, s[18:19]
	global_store_dwordx2 v[40:41], v[32:33], off
	s_waitcnt lgkmcnt(6)
	v_sub_f32_e32 v21, v21, v44
	v_sub_f32_e32 v20, v20, v44
	v_sub_f32_e32 v23, v23, v44
	v_sub_f32_e32 v22, v22, v44
	v_pk_mul_f32 v[22:23], v[44:45], v[22:23] op_sel:[1,0]
	v_pk_mul_f32 v[20:21], v[44:45], v[20:21] op_sel:[1,0]
	s_waitcnt lgkmcnt(5)
	v_sub_f32_e32 v25, v25, v46
	v_sub_f32_e32 v24, v24, v46
	v_sub_f32_e32 v27, v27, v46
	v_sub_f32_e32 v26, v26, v46
	v_pk_fma_f32 v[20:21], v[120:121], v[20:21], v[124:125]
	v_pk_fma_f32 v[22:23], v[122:123], v[22:23], v[126:127]
	v_pk_mul_f32 v[26:27], v[46:47], v[26:27] op_sel:[1,0]
	v_pk_mul_f32 v[24:25], v[46:47], v[24:25] op_sel:[1,0]
	v_pk_fma_f32 v[26:27], v[122:123], v[26:27], v[126:127]
	v_pk_fma_f32 v[24:25], v[120:121], v[24:25], v[124:125]
	v_cndmask_b32_e32 v23, v245, v23, vcc
	v_cndmask_b32_e32 v22, v245, v22, vcc
	v_cndmask_b32_e32 v21, v245, v21, vcc
	v_cndmask_b32_e32 v20, v245, v20, vcc
	v_cndmask_b32_e32 v27, v245, v27, vcc
	v_cndmask_b32_e32 v26, v245, v26, vcc
	v_cndmask_b32_e32 v25, v245, v25, vcc
	v_cndmask_b32_e32 v24, v245, v24, vcc
	global_store_dwordx4 v[36:37], v[20:23], off offset:512 sc0 sc1 nt
	global_store_dwordx4 v[38:39], v[24:27], off offset:512 sc0 sc1 nt
	s_nop 0
	v_pk_fma_f32 v[22:23], v[162:163], v[22:23], v[114:115]
	v_pk_fma_f32 v[20:21], v[160:161], v[20:21], v[112:113]
	v_pk_fma_f32 v[26:27], v[162:163], v[26:27], v[114:115]
	v_pk_fma_f32 v[24:25], v[160:161], v[24:25], v[112:113]
	v_cvt_pk_bf16_f32 v20, v20, v21
	v_cvt_pk_bf16_f32 v21, v22, v23
	s_nop 0
	v_cvt_pk_bf16_f32 v22, v24, v25
	v_cvt_pk_bf16_f32 v23, v26, v27
	ds_write_b128 v180, v[4:7]
	ds_write_b128 v180, v[8:11] offset:64
	ds_read_b128 v[4:7], v182
	ds_read_b128 v[8:11], v182 offset:1152
	global_store_dwordx2 v[34:35], v[20:21], off offset:256
	global_store_dwordx2 v[40:41], v[22:23], off offset:256
	s_add_u32 s18, s5, s78
	s_addc_u32 s19, s20, s79
	v_lshl_add_u64 v[20:21], s[18:19], 0, v[130:131]
	s_waitcnt lgkmcnt(4)
	v_sub_f32_e32 v13, v13, v28
	v_sub_f32_e32 v12, v12, v28
	v_sub_f32_e32 v15, v15, v28
	v_sub_f32_e32 v14, v14, v28
	v_sub_f32_e32 v17, v17, v30
	v_sub_f32_e32 v16, v16, v30
	v_sub_f32_e32 v19, v19, v30
	v_sub_f32_e32 v18, v18, v30
	v_add_co_u32_e64 v24, s[18:19], s71, v20
	v_pk_mul_f32 v[14:15], v[28:29], v[14:15] op_sel:[1,0]
	v_pk_mul_f32 v[12:13], v[28:29], v[12:13] op_sel:[1,0]
	v_pk_mul_f32 v[18:19], v[30:31], v[18:19] op_sel:[1,0]
	v_pk_mul_f32 v[16:17], v[30:31], v[16:17] op_sel:[1,0]
	v_addc_co_u32_e64 v25, s[18:19], 0, v21, s[18:19]
	v_pk_fma_f32 v[12:13], v[148:149], v[12:13], v[152:153]
	v_pk_fma_f32 v[14:15], v[150:151], v[14:15], v[154:155]
	v_pk_fma_f32 v[16:17], v[148:149], v[16:17], v[152:153]
	v_pk_fma_f32 v[18:19], v[150:151], v[18:19], v[154:155]
	s_add_i32 s18, s82, s70
	v_cndmask_b32_e32 v15, v245, v15, vcc
	v_cndmask_b32_e32 v14, v245, v14, vcc
	v_cndmask_b32_e32 v13, v245, v13, vcc
	v_cndmask_b32_e32 v12, v245, v12, vcc
	v_cndmask_b32_e32 v19, v245, v19, vcc
	v_cndmask_b32_e32 v18, v245, v18, vcc
	v_cndmask_b32_e32 v17, v245, v17, vcc
	v_cndmask_b32_e32 v16, v245, v16, vcc
	s_ashr_i32 s19, s18, 31
	global_store_dwordx4 v[20:21], v[12:15], off sc0 sc1 nt
	global_store_dwordx4 v[24:25], v[16:19], off sc0 sc1 nt
	s_lshl_b64 s[18:19], s[18:19], 12
	v_pk_fma_f32 v[14:15], v[158:159], v[14:15], v[142:143]
	v_pk_fma_f32 v[12:13], v[156:157], v[12:13], v[140:141]
	v_pk_fma_f32 v[16:17], v[156:157], v[16:17], v[140:141]
	v_cvt_pk_bf16_f32 v12, v12, v13
	v_cvt_pk_bf16_f32 v13, v14, v15
	v_pk_fma_f32 v[18:19], v[158:159], v[18:19], v[142:143]
	v_cvt_pk_bf16_f32 v14, v16, v17
	v_lshl_add_u64 v[16:17], v[128:129], 0, s[18:19]
	v_cvt_pk_bf16_f32 v15, v18, v19
	global_store_dwordx2 v[16:17], v[12:13], off
	v_add_co_u32_e64 v12, s[18:19], s83, v16
	v_lshl_add_u64 v[22:23], v[20:21], 0, s[76:77]
	s_nop 0
	v_addc_co_u32_e64 v13, s[18:19], 0, v17, s[18:19]
	global_store_dwordx2 v[12:13], v[14:15], off
	s_waitcnt lgkmcnt(1)
	v_sub_f32_e32 v5, v5, v28
	v_sub_f32_e32 v4, v4, v28
	v_sub_f32_e32 v7, v7, v28
	v_sub_f32_e32 v6, v6, v28
	v_pk_mul_f32 v[6:7], v[28:29], v[6:7] op_sel:[1,0]
	v_pk_mul_f32 v[4:5], v[28:29], v[4:5] op_sel:[1,0]
	s_waitcnt lgkmcnt(0)
	v_sub_f32_e32 v9, v9, v30
	v_sub_f32_e32 v8, v8, v30
	v_sub_f32_e32 v11, v11, v30
	v_sub_f32_e32 v10, v10, v30
	v_pk_fma_f32 v[4:5], v[120:121], v[4:5], v[124:125]
	v_pk_fma_f32 v[6:7], v[122:123], v[6:7], v[126:127]
	v_pk_mul_f32 v[10:11], v[30:31], v[10:11] op_sel:[1,0]
	v_pk_mul_f32 v[8:9], v[30:31], v[8:9] op_sel:[1,0]
	v_pk_fma_f32 v[10:11], v[122:123], v[10:11], v[126:127]
	v_pk_fma_f32 v[8:9], v[120:121], v[8:9], v[124:125]
	v_cndmask_b32_e32 v7, v245, v7, vcc
	v_cndmask_b32_e32 v6, v245, v6, vcc
	v_cndmask_b32_e32 v5, v245, v5, vcc
	v_cndmask_b32_e32 v4, v245, v4, vcc
	v_cndmask_b32_e32 v11, v245, v11, vcc
	v_cndmask_b32_e32 v10, v245, v10, vcc
	v_cndmask_b32_e32 v9, v245, v9, vcc
	v_cndmask_b32_e32 v8, v245, v8, vcc
	global_store_dwordx4 v[20:21], v[4:7], off offset:512 sc0 sc1 nt
	global_store_dwordx4 v[22:23], v[8:11], off offset:512 sc0 sc1 nt
	s_andn2_b64 vcc, exec, s[16:17]
	v_pk_fma_f32 v[4:5], v[160:161], v[4:5], v[112:113]
	v_pk_fma_f32 v[6:7], v[162:163], v[6:7], v[114:115]
	v_cvt_pk_bf16_f32 v4, v4, v5
	v_pk_fma_f32 v[10:11], v[162:163], v[10:11], v[114:115]
	v_cvt_pk_bf16_f32 v5, v6, v7
	v_pk_fma_f32 v[8:9], v[160:161], v[8:9], v[112:113]
	s_mov_b64 s[16:17], -1
	v_cvt_pk_bf16_f32 v6, v8, v9
	v_cvt_pk_bf16_f32 v7, v10, v11
	global_store_dwordx2 v[16:17], v[4:5], off offset:256
	global_store_dwordx2 v[12:13], v[6:7], off offset:256
	s_cbranch_vccnz .LBB0_636
	v_readlane_b32 s16, v254, 38
	v_readlane_b32 s17, v254, 39
	s_andn2_b64 vcc, exec, s[16:17]
	s_cbranch_vccnz .LBB0_635
	s_barrier
	s_branch .LBB0_635

.LBB0_861:
	s_or_b64 exec, exec, s[22:23]
	s_waitcnt lgkmcnt(0)
	s_barrier
	ds_write_b128 v182, v[140:143]
	ds_write_b128 v182, v[144:147] offset:64
	s_waitcnt lgkmcnt(2)
	v_cmp_eq_u32_e64 s[20:21], 0, v159
	v_add_u32_e32 v176, v158, v185
	ds_read_b128 v[156:159], v184
	ds_read_b128 v[192:195], v184 offset:1152
	ds_read2_b64 v[140:143], v187 offset1:8
	ds_write_b128 v182, v[148:151]
	ds_write_b128 v182, v[152:155] offset:64
	ds_read_b128 v[148:151], v184
	ds_read_b128 v[144:147], v184 offset:1152
	v_ashrrev_i32_e32 v177, 31, v176
	s_add_u32 s6, s24, s50
	v_lshl_add_u64 v[152:153], v[176:177], 1, s[26:27]
	s_mov_b64 s[22:23], 0xac00000
	s_addc_u32 s7, s25, s51
	v_lshl_add_u64 v[174:175], v[152:153], 0, s[22:23]
	s_add_u32 s22, s6, s36
	s_addc_u32 s23, s7, s37
	s_waitcnt lgkmcnt(4)
	v_sub_f32_e32 v153, v157, v140
	v_sub_f32_e32 v152, v156, v140
	v_sub_f32_e32 v155, v159, v140
	v_sub_f32_e32 v154, v158, v140
	v_sub_f32_e32 v157, v193, v142
	v_sub_f32_e32 v156, v192, v142
	v_sub_f32_e32 v159, v195, v142
	v_sub_f32_e32 v158, v194, v142
	v_lshl_add_u64 v[178:179], v[176:177], 2, s[22:23]
	v_pk_mul_f32 v[154:155], v[140:141], v[154:155] op_sel:[1,0]
	v_pk_mul_f32 v[152:153], v[140:141], v[152:153] op_sel:[1,0]
	v_pk_mul_f32 v[158:159], v[142:143], v[158:159] op_sel:[1,0]
	v_pk_mul_f32 v[156:157], v[142:143], v[156:157] op_sel:[1,0]
	v_add_co_u32_e32 v192, vcc, 0x10000, v178
	s_waitcnt vmcnt(2)
	v_pk_fma_f32 v[152:153], v[104:105], v[152:153], v[112:113]
	v_pk_fma_f32 v[154:155], v[106:107], v[154:155], v[114:115]
	v_pk_fma_f32 v[156:157], v[104:105], v[156:157], v[112:113]
	v_pk_fma_f32 v[158:159], v[106:107], v[158:159], v[114:115]
	v_addc_co_u32_e32 v193, vcc, 0, v179, vcc
	v_cndmask_b32_e64 v155, v245, v155, s[20:21]
	v_cndmask_b32_e64 v154, v245, v154, s[20:21]
	v_cndmask_b32_e64 v153, v245, v153, s[20:21]
	v_cndmask_b32_e64 v152, v245, v152, s[20:21]
	v_cndmask_b32_e64 v159, v245, v159, s[20:21]
	v_cndmask_b32_e64 v158, v245, v158, s[20:21]
	v_cndmask_b32_e64 v157, v245, v157, s[20:21]
	v_cndmask_b32_e64 v156, v245, v156, s[20:21]
	s_and_b64 vcc, exec, s[18:19]
	global_store_dwordx4 v[178:179], v[152:155], off sc0 sc1 nt
	global_store_dwordx4 v[192:193], v[156:159], off sc0 sc1 nt
	s_cbranch_vccnz .LBB0_863
	s_add_i32 s22, s68, s30
	s_ashr_i32 s23, s22, 31
	v_pk_fma_f32 v[154:155], v[172:173], v[154:155], v[102:103]
	v_pk_fma_f32 v[152:153], v[170:171], v[152:153], v[100:101]
	v_pk_fma_f32 v[156:157], v[170:171], v[156:157], v[100:101]
	s_lshl_b64 s[22:23], s[22:23], 12
	v_cvt_pk_bf16_f32 v152, v152, v153
	v_cvt_pk_bf16_f32 v153, v154, v155
	v_cvt_pk_bf16_f32 v154, v156, v157
	v_lshl_add_u64 v[156:157], v[174:175], 0, s[22:23]
	v_pk_fma_f32 v[158:159], v[172:173], v[158:159], v[102:103]
	s_nop 0
	v_cvt_pk_bf16_f32 v155, v158, v159
	global_store_dwordx2 v[156:157], v[152:153], off
	v_add_co_u32_e32 v152, vcc, 0x8000, v156
	s_nop 1
	v_addc_co_u32_e32 v153, vcc, 0, v157, vcc
	global_store_dwordx2 v[152:153], v[154:155], off
.LBB0_863:
	ds_write_b128 v182, v[132:135]
	ds_write_b128 v182, v[136:139] offset:64
	ds_read_b128 v[152:155], v184
	ds_read_b128 v[136:139], v184 offset:1152
	ds_read2_b64 v[132:135], v187 offset0:16 offset1:24
	v_mov_b32_e32 v156, v141
	v_mov_b32_e32 v157, v141
	v_mov_b32_e32 v158, v143
	v_mov_b32_e32 v159, v143
	v_lshl_add_u64 v[192:193], v[178:179], 0, s[76:77]
	s_waitcnt lgkmcnt(6)
	v_sub_f32_e32 v149, v149, v140
	v_sub_f32_e32 v148, v148, v140
	v_sub_f32_e32 v151, v151, v140
	v_sub_f32_e32 v150, v150, v140
	v_mov_b32_e32 v140, v141
	s_waitcnt lgkmcnt(5)
	v_sub_f32_e32 v145, v145, v142
	v_sub_f32_e32 v144, v144, v142
	v_sub_f32_e32 v147, v147, v142
	v_sub_f32_e32 v146, v146, v142
	v_mov_b32_e32 v142, v143
	v_pk_mul_f32 v[140:141], v[140:141], v[150:151]
	v_pk_mul_f32 v[148:149], v[156:157], v[148:149]
	v_pk_mul_f32 v[142:143], v[142:143], v[146:147]
	v_pk_mul_f32 v[144:145], v[158:159], v[144:145]
	s_waitcnt vmcnt(2)
	v_pk_fma_f32 v[148:149], v[88:89], v[148:149], v[92:93]
	v_pk_fma_f32 v[140:141], v[90:91], v[140:141], v[94:95]
	v_pk_fma_f32 v[144:145], v[88:89], v[144:145], v[92:93]
	v_pk_fma_f32 v[146:147], v[90:91], v[142:143], v[94:95]
	v_cndmask_b32_e64 v143, v245, v141, s[20:21]
	v_cndmask_b32_e64 v142, v245, v140, s[20:21]
	v_cndmask_b32_e64 v141, v245, v149, s[20:21]
	v_cndmask_b32_e64 v140, v245, v148, s[20:21]
	v_cndmask_b32_e64 v147, v245, v147, s[20:21]
	v_cndmask_b32_e64 v146, v245, v146, s[20:21]
	v_cndmask_b32_e64 v145, v245, v145, s[20:21]
	v_cndmask_b32_e64 v144, v245, v144, s[20:21]
	s_and_b64 vcc, exec, s[18:19]
	global_store_dwordx4 v[178:179], v[140:143], off offset:512 sc0 sc1 nt
	global_store_dwordx4 v[192:193], v[144:147], off offset:512 sc0 sc1 nt
	s_cbranch_vccnz .LBB0_865
	s_add_i32 s22, s68, s30
	s_ashr_i32 s23, s22, 31
	v_pk_fma_f32 v[142:143], v[168:169], v[142:143], v[78:79]
	v_pk_fma_f32 v[140:141], v[166:167], v[140:141], v[76:77]
	v_pk_fma_f32 v[144:145], v[166:167], v[144:145], v[76:77]
	s_lshl_b64 s[22:23], s[22:23], 12
	v_cvt_pk_bf16_f32 v140, v140, v141
	v_cvt_pk_bf16_f32 v141, v142, v143
	v_cvt_pk_bf16_f32 v142, v144, v145
	v_lshl_add_u64 v[144:145], v[174:175], 0, s[22:23]
	v_pk_fma_f32 v[146:147], v[168:169], v[146:147], v[78:79]
	s_nop 0
	v_cvt_pk_bf16_f32 v143, v146, v147
	global_store_dwordx2 v[144:145], v[140:141], off offset:256
	v_add_co_u32_e32 v140, vcc, 0x8000, v144
	s_nop 1
	v_addc_co_u32_e32 v141, vcc, 0, v145, vcc
	global_store_dwordx2 v[140:141], v[142:143], off offset:256
.LBB0_865:
	ds_write_b128 v182, v[124:127]
	ds_write_b128 v182, v[128:131] offset:64
	ds_read_b128 v[128:131], v184
	ds_read_b128 v[124:127], v184 offset:1152
	s_waitcnt lgkmcnt(4)
	v_sub_f32_e32 v141, v153, v132
	v_sub_f32_e32 v140, v152, v132
	v_sub_f32_e32 v137, v137, v134
	v_sub_f32_e32 v136, v136, v134
	s_add_u32 s22, s6, s42
	v_sub_f32_e32 v143, v155, v132
	v_sub_f32_e32 v142, v154, v132
	v_pk_mul_f32 v[140:141], v[132:133], v[140:141] op_sel:[1,0]
	v_sub_f32_e32 v139, v139, v134
	v_sub_f32_e32 v138, v138, v134
	v_pk_mul_f32 v[136:137], v[134:135], v[136:137] op_sel:[1,0]
	s_addc_u32 s23, s7, s43
	v_pk_mul_f32 v[142:143], v[132:133], v[142:143] op_sel:[1,0]
	v_pk_fma_f32 v[140:141], v[104:105], v[140:141], v[112:113]
	v_pk_mul_f32 v[138:139], v[134:135], v[138:139] op_sel:[1,0]
	v_pk_fma_f32 v[144:145], v[104:105], v[136:137], v[112:113]
	v_pk_fma_f32 v[142:143], v[106:107], v[142:143], v[114:115]
	v_pk_fma_f32 v[146:147], v[106:107], v[138:139], v[114:115]
	v_cndmask_b32_e64 v137, v245, v141, s[20:21]
	v_cndmask_b32_e64 v136, v245, v140, s[20:21]
	v_cndmask_b32_e64 v141, v245, v145, s[20:21]
	v_cndmask_b32_e64 v140, v245, v144, s[20:21]
	v_lshl_add_u64 v[144:145], v[176:177], 2, s[22:23]
	v_cndmask_b32_e64 v138, v245, v142, s[20:21]
	v_cndmask_b32_e64 v142, v245, v146, s[20:21]
	v_add_co_u32_e32 v146, vcc, 0x10000, v144
	v_cndmask_b32_e64 v139, v245, v143, s[20:21]
	v_cndmask_b32_e64 v143, v245, v147, s[20:21]
	v_addc_co_u32_e32 v147, vcc, 0, v145, vcc
	s_and_b64 vcc, exec, s[18:19]
	global_store_dwordx4 v[144:145], v[136:139], off sc0 sc1 nt
	global_store_dwordx4 v[146:147], v[140:143], off sc0 sc1 nt
	s_cbranch_vccnz .LBB0_867
	v_readlane_b32 s22, v254, 48
	v_readlane_b32 s23, v254, 49
	s_add_i32 s22, s68, s22
	s_ashr_i32 s23, s22, 31
	v_pk_fma_f32 v[138:139], v[172:173], v[138:139], v[102:103]
	v_pk_fma_f32 v[136:137], v[170:171], v[136:137], v[100:101]
	v_pk_fma_f32 v[140:141], v[170:171], v[140:141], v[100:101]
	s_lshl_b64 s[22:23], s[22:23], 12
	v_cvt_pk_bf16_f32 v136, v136, v137
	v_cvt_pk_bf16_f32 v137, v138, v139
	v_cvt_pk_bf16_f32 v138, v140, v141
	v_lshl_add_u64 v[140:141], v[174:175], 0, s[22:23]
	v_pk_fma_f32 v[142:143], v[172:173], v[142:143], v[102:103]
	s_nop 0
	v_cvt_pk_bf16_f32 v139, v142, v143
	global_store_dwordx2 v[140:141], v[136:137], off
	v_add_co_u32_e32 v136, vcc, 0x8000, v140
	s_nop 1
	v_addc_co_u32_e32 v137, vcc, 0, v141, vcc
	global_store_dwordx2 v[136:137], v[138:139], off
.LBB0_867:
	ds_write_b128 v182, v[116:119]
	ds_write_b128 v182, v[120:123] offset:64
	ds_read_b128 v[136:139], v184
	ds_read_b128 v[120:123], v184 offset:1152
	ds_read2_b64 v[116:119], v187 offset0:32 offset1:40
	v_mov_b32_e32 v140, v133
	v_mov_b32_e32 v141, v133
	v_mov_b32_e32 v142, v135
	v_mov_b32_e32 v143, v135
	v_lshl_add_u64 v[146:147], v[144:145], 0, s[76:77]
	s_waitcnt lgkmcnt(6)
	v_sub_f32_e32 v129, v129, v132
	v_sub_f32_e32 v128, v128, v132
	v_sub_f32_e32 v131, v131, v132
	v_sub_f32_e32 v130, v130, v132
	v_mov_b32_e32 v132, v133
	s_waitcnt lgkmcnt(5)
	v_sub_f32_e32 v125, v125, v134
	v_sub_f32_e32 v124, v124, v134
	v_sub_f32_e32 v127, v127, v134
	v_sub_f32_e32 v126, v126, v134
	v_mov_b32_e32 v134, v135
	v_pk_mul_f32 v[130:131], v[132:133], v[130:131]
	v_pk_mul_f32 v[128:129], v[140:141], v[128:129]
	v_pk_mul_f32 v[126:127], v[134:135], v[126:127]
	v_pk_mul_f32 v[124:125], v[142:143], v[124:125]
	v_pk_fma_f32 v[128:129], v[88:89], v[128:129], v[92:93]
	v_pk_fma_f32 v[130:131], v[90:91], v[130:131], v[94:95]
	v_pk_fma_f32 v[132:133], v[88:89], v[124:125], v[92:93]
	v_pk_fma_f32 v[134:135], v[90:91], v[126:127], v[94:95]
	v_cndmask_b32_e64 v127, v245, v131, s[20:21]
	v_cndmask_b32_e64 v126, v245, v130, s[20:21]
	v_cndmask_b32_e64 v125, v245, v129, s[20:21]
	v_cndmask_b32_e64 v124, v245, v128, s[20:21]
	v_cndmask_b32_e64 v131, v245, v135, s[20:21]
	v_cndmask_b32_e64 v130, v245, v134, s[20:21]
	v_cndmask_b32_e64 v129, v245, v133, s[20:21]
	v_cndmask_b32_e64 v128, v245, v132, s[20:21]
	s_and_b64 vcc, exec, s[18:19]
	global_store_dwordx4 v[144:145], v[124:127], off offset:512 sc0 sc1 nt
	global_store_dwordx4 v[146:147], v[128:131], off offset:512 sc0 sc1 nt
	s_cbranch_vccnz .LBB0_869
	v_readlane_b32 s22, v254, 48
	v_readlane_b32 s23, v254, 49
	s_add_i32 s22, s68, s22
	s_ashr_i32 s23, s22, 31
	v_pk_fma_f32 v[126:127], v[168:169], v[126:127], v[78:79]
	v_pk_fma_f32 v[124:125], v[166:167], v[124:125], v[76:77]
	v_pk_fma_f32 v[128:129], v[166:167], v[128:129], v[76:77]
	s_lshl_b64 s[22:23], s[22:23], 12
	v_cvt_pk_bf16_f32 v124, v124, v125
	v_cvt_pk_bf16_f32 v125, v126, v127
	v_cvt_pk_bf16_f32 v126, v128, v129
	v_lshl_add_u64 v[128:129], v[174:175], 0, s[22:23]
	v_pk_fma_f32 v[130:131], v[168:169], v[130:131], v[78:79]
	s_nop 0
	v_cvt_pk_bf16_f32 v127, v130, v131
	global_store_dwordx2 v[128:129], v[124:125], off offset:256
	v_add_co_u32_e32 v124, vcc, 0x8000, v128
	s_nop 1
	v_addc_co_u32_e32 v125, vcc, 0, v129, vcc
	global_store_dwordx2 v[124:125], v[126:127], off offset:256
.LBB0_869:
	ds_write_b128 v182, v[96:99]
	ds_write_b128 v182, v[108:111] offset:64
	ds_read_b128 v[108:111], v184
	ds_read_b128 v[96:99], v184 offset:1152
	s_waitcnt lgkmcnt(4)
	v_sub_f32_e32 v125, v137, v116
	v_sub_f32_e32 v124, v136, v116
	v_sub_f32_e32 v121, v121, v118
	v_sub_f32_e32 v120, v120, v118
	s_add_u32 s22, s6, s48
	v_sub_f32_e32 v127, v139, v116
	v_sub_f32_e32 v126, v138, v116
	v_pk_mul_f32 v[124:125], v[116:117], v[124:125] op_sel:[1,0]
	v_sub_f32_e32 v123, v123, v118
	v_sub_f32_e32 v122, v122, v118
	v_pk_mul_f32 v[120:121], v[118:119], v[120:121] op_sel:[1,0]
	s_addc_u32 s23, s7, s49
	v_pk_mul_f32 v[126:127], v[116:117], v[126:127] op_sel:[1,0]
	v_pk_fma_f32 v[124:125], v[104:105], v[124:125], v[112:113]
	v_pk_mul_f32 v[122:123], v[118:119], v[122:123] op_sel:[1,0]
	v_pk_fma_f32 v[128:129], v[104:105], v[120:121], v[112:113]
	v_pk_fma_f32 v[126:127], v[106:107], v[126:127], v[114:115]
	v_pk_fma_f32 v[130:131], v[106:107], v[122:123], v[114:115]
	v_cndmask_b32_e64 v121, v245, v125, s[20:21]
	v_cndmask_b32_e64 v120, v245, v124, s[20:21]
	v_cndmask_b32_e64 v125, v245, v129, s[20:21]
	v_cndmask_b32_e64 v124, v245, v128, s[20:21]
	v_lshl_add_u64 v[128:129], v[176:177], 2, s[22:23]
	v_cndmask_b32_e64 v122, v245, v126, s[20:21]
	v_cndmask_b32_e64 v126, v245, v130, s[20:21]
	v_add_co_u32_e32 v130, vcc, 0x10000, v128
	v_cndmask_b32_e64 v123, v245, v127, s[20:21]
	v_cndmask_b32_e64 v127, v245, v131, s[20:21]
	v_addc_co_u32_e32 v131, vcc, 0, v129, vcc
	s_and_b64 vcc, exec, s[18:19]
	global_store_dwordx4 v[128:129], v[120:123], off sc0 sc1 nt
	global_store_dwordx4 v[130:131], v[124:127], off sc0 sc1 nt
	s_cbranch_vccnz .LBB0_871
	v_readlane_b32 s22, v254, 52
	v_readlane_b32 s23, v254, 53
	s_add_i32 s22, s68, s22
	s_ashr_i32 s23, s22, 31
	v_pk_fma_f32 v[122:123], v[172:173], v[122:123], v[102:103]
	v_pk_fma_f32 v[120:121], v[170:171], v[120:121], v[100:101]
	v_pk_fma_f32 v[124:125], v[170:171], v[124:125], v[100:101]
	s_lshl_b64 s[22:23], s[22:23], 12
	v_cvt_pk_bf16_f32 v120, v120, v121
	v_cvt_pk_bf16_f32 v121, v122, v123
	v_cvt_pk_bf16_f32 v122, v124, v125
	v_lshl_add_u64 v[124:125], v[174:175], 0, s[22:23]
	v_pk_fma_f32 v[126:127], v[172:173], v[126:127], v[102:103]
	s_nop 0
	v_cvt_pk_bf16_f32 v123, v126, v127
	global_store_dwordx2 v[124:125], v[120:121], off
	v_add_co_u32_e32 v120, vcc, 0x8000, v124
	s_nop 1
	v_addc_co_u32_e32 v121, vcc, 0, v125, vcc
	global_store_dwordx2 v[120:121], v[122:123], off
.LBB0_871:
	ds_write_b128 v182, v[80:83]
	ds_write_b128 v182, v[84:87] offset:64
	ds_read_b128 v[120:123], v184
	ds_read_b128 v[84:87], v184 offset:1152
	ds_read2_b64 v[80:83], v187 offset0:48 offset1:56
	v_mov_b32_e32 v124, v117
	v_mov_b32_e32 v125, v117
	v_mov_b32_e32 v126, v119
	v_mov_b32_e32 v127, v119
	v_lshl_add_u64 v[130:131], v[128:129], 0, s[76:77]
	s_waitcnt lgkmcnt(6)
	v_sub_f32_e32 v109, v109, v116
	v_sub_f32_e32 v108, v108, v116
	v_sub_f32_e32 v111, v111, v116
	v_sub_f32_e32 v110, v110, v116
	v_mov_b32_e32 v116, v117
	s_waitcnt lgkmcnt(5)
	v_sub_f32_e32 v97, v97, v118
	v_sub_f32_e32 v96, v96, v118
	v_sub_f32_e32 v99, v99, v118
	v_sub_f32_e32 v98, v98, v118
	v_mov_b32_e32 v118, v119
	v_pk_mul_f32 v[110:111], v[116:117], v[110:111]
	v_pk_mul_f32 v[108:109], v[124:125], v[108:109]
	v_pk_mul_f32 v[98:99], v[118:119], v[98:99]
	v_pk_mul_f32 v[96:97], v[126:127], v[96:97]
	v_pk_fma_f32 v[108:109], v[88:89], v[108:109], v[92:93]
	v_pk_fma_f32 v[110:111], v[90:91], v[110:111], v[94:95]
	v_pk_fma_f32 v[116:117], v[88:89], v[96:97], v[92:93]
	v_pk_fma_f32 v[118:119], v[90:91], v[98:99], v[94:95]
	v_cndmask_b32_e64 v99, v245, v111, s[20:21]
	v_cndmask_b32_e64 v98, v245, v110, s[20:21]
	v_cndmask_b32_e64 v97, v245, v109, s[20:21]
	v_cndmask_b32_e64 v96, v245, v108, s[20:21]
	v_cndmask_b32_e64 v111, v245, v119, s[20:21]
	v_cndmask_b32_e64 v110, v245, v118, s[20:21]
	v_cndmask_b32_e64 v109, v245, v117, s[20:21]
	v_cndmask_b32_e64 v108, v245, v116, s[20:21]
	s_and_b64 vcc, exec, s[18:19]
	global_store_dwordx4 v[128:129], v[96:99], off offset:512 sc0 sc1 nt
	global_store_dwordx4 v[130:131], v[108:111], off offset:512 sc0 sc1 nt
	s_cbranch_vccnz .LBB0_873
	v_readlane_b32 s22, v254, 52
	v_readlane_b32 s23, v254, 53
	s_add_i32 s22, s68, s22
	s_ashr_i32 s23, s22, 31
	v_pk_fma_f32 v[98:99], v[168:169], v[98:99], v[78:79]
	v_pk_fma_f32 v[96:97], v[166:167], v[96:97], v[76:77]
	v_pk_fma_f32 v[108:109], v[166:167], v[108:109], v[76:77]
	s_lshl_b64 s[22:23], s[22:23], 12
	v_cvt_pk_bf16_f32 v96, v96, v97
	v_cvt_pk_bf16_f32 v97, v98, v99
	v_cvt_pk_bf16_f32 v98, v108, v109
	v_lshl_add_u64 v[108:109], v[174:175], 0, s[22:23]
	v_pk_fma_f32 v[110:111], v[168:169], v[110:111], v[78:79]
	s_nop 0
	v_cvt_pk_bf16_f32 v99, v110, v111
	global_store_dwordx2 v[108:109], v[96:97], off offset:256
	v_add_co_u32_e32 v96, vcc, 0x8000, v108
	s_nop 1
	v_addc_co_u32_e32 v97, vcc, 0, v109, vcc
	global_store_dwordx2 v[96:97], v[98:99], off offset:256
.LBB0_873:
	ds_write_b128 v182, v[68:71]
	ds_write_b128 v182, v[72:75] offset:64
	ds_read_b128 v[72:75], v184
	ds_read_b128 v[68:71], v184 offset:1152
	s_waitcnt lgkmcnt(4)
	v_sub_f32_e32 v97, v121, v80
	v_sub_f32_e32 v96, v120, v80
	v_sub_f32_e32 v85, v85, v82
	v_sub_f32_e32 v84, v84, v82
	s_add_u32 s22, s6, s54
	v_sub_f32_e32 v99, v123, v80
	v_sub_f32_e32 v98, v122, v80
	v_pk_mul_f32 v[96:97], v[80:81], v[96:97] op_sel:[1,0]
	v_sub_f32_e32 v87, v87, v82
	v_sub_f32_e32 v86, v86, v82
	v_pk_mul_f32 v[84:85], v[82:83], v[84:85] op_sel:[1,0]
	s_addc_u32 s23, s7, s55
	v_pk_mul_f32 v[98:99], v[80:81], v[98:99] op_sel:[1,0]
	v_pk_fma_f32 v[96:97], v[104:105], v[96:97], v[112:113]
	v_pk_mul_f32 v[86:87], v[82:83], v[86:87] op_sel:[1,0]
	v_pk_fma_f32 v[108:109], v[104:105], v[84:85], v[112:113]
	v_pk_fma_f32 v[98:99], v[106:107], v[98:99], v[114:115]
	v_pk_fma_f32 v[110:111], v[106:107], v[86:87], v[114:115]
	v_cndmask_b32_e64 v85, v245, v97, s[20:21]
	v_cndmask_b32_e64 v84, v245, v96, s[20:21]
	v_cndmask_b32_e64 v97, v245, v109, s[20:21]
	v_cndmask_b32_e64 v96, v245, v108, s[20:21]
	v_lshl_add_u64 v[108:109], v[176:177], 2, s[22:23]
	v_cndmask_b32_e64 v86, v245, v98, s[20:21]
	v_cndmask_b32_e64 v98, v245, v110, s[20:21]
	v_add_co_u32_e32 v110, vcc, 0x10000, v108
	v_cndmask_b32_e64 v87, v245, v99, s[20:21]
	v_cndmask_b32_e64 v99, v245, v111, s[20:21]
	v_addc_co_u32_e32 v111, vcc, 0, v109, vcc
	s_and_b64 vcc, exec, s[18:19]
	global_store_dwordx4 v[108:109], v[84:87], off sc0 sc1 nt
	global_store_dwordx4 v[110:111], v[96:99], off sc0 sc1 nt
	s_cbranch_vccnz .LBB0_875
	v_readlane_b32 s22, v254, 56
	v_readlane_b32 s23, v254, 57
	s_add_i32 s22, s68, s22
	s_ashr_i32 s23, s22, 31
	v_pk_fma_f32 v[86:87], v[172:173], v[86:87], v[102:103]
	v_pk_fma_f32 v[84:85], v[170:171], v[84:85], v[100:101]
	v_pk_fma_f32 v[96:97], v[170:171], v[96:97], v[100:101]
	s_lshl_b64 s[22:23], s[22:23], 12
	v_cvt_pk_bf16_f32 v84, v84, v85
	v_cvt_pk_bf16_f32 v85, v86, v87
	v_cvt_pk_bf16_f32 v86, v96, v97
	v_lshl_add_u64 v[96:97], v[174:175], 0, s[22:23]
	v_pk_fma_f32 v[98:99], v[172:173], v[98:99], v[102:103]
	s_nop 0
	v_cvt_pk_bf16_f32 v87, v98, v99
	global_store_dwordx2 v[96:97], v[84:85], off
	v_add_co_u32_e32 v84, vcc, 0x8000, v96
	s_nop 1
	v_addc_co_u32_e32 v85, vcc, 0, v97, vcc
	global_store_dwordx2 v[84:85], v[86:87], off
.LBB0_875:
	ds_write_b128 v182, v[60:63]
	ds_write_b128 v182, v[64:67] offset:64
	ds_read_b128 v[84:87], v184
	ds_read_b128 v[64:67], v184 offset:1152
	ds_read2_b64 v[60:63], v187 offset0:128 offset1:136
	v_mov_b32_e32 v96, v81
	v_mov_b32_e32 v97, v81
	v_mov_b32_e32 v98, v83
	v_mov_b32_e32 v99, v83
	v_lshl_add_u64 v[110:111], v[108:109], 0, s[76:77]
	s_waitcnt lgkmcnt(6)
	v_sub_f32_e32 v73, v73, v80
	v_sub_f32_e32 v72, v72, v80
	v_sub_f32_e32 v75, v75, v80
	v_sub_f32_e32 v74, v74, v80
	v_mov_b32_e32 v80, v81
	s_waitcnt lgkmcnt(5)
	v_sub_f32_e32 v69, v69, v82
	v_sub_f32_e32 v68, v68, v82
	v_sub_f32_e32 v71, v71, v82
	v_sub_f32_e32 v70, v70, v82
	v_mov_b32_e32 v82, v83
	v_pk_mul_f32 v[74:75], v[80:81], v[74:75]
	v_pk_mul_f32 v[72:73], v[96:97], v[72:73]
	v_pk_mul_f32 v[70:71], v[82:83], v[70:71]
	v_pk_mul_f32 v[68:69], v[98:99], v[68:69]
	v_pk_fma_f32 v[72:73], v[88:89], v[72:73], v[92:93]
	v_pk_fma_f32 v[74:75], v[90:91], v[74:75], v[94:95]
	v_pk_fma_f32 v[80:81], v[88:89], v[68:69], v[92:93]
	v_pk_fma_f32 v[82:83], v[90:91], v[70:71], v[94:95]
	v_cndmask_b32_e64 v71, v245, v75, s[20:21]
	v_cndmask_b32_e64 v70, v245, v74, s[20:21]
	v_cndmask_b32_e64 v69, v245, v73, s[20:21]
	v_cndmask_b32_e64 v68, v245, v72, s[20:21]
	v_cndmask_b32_e64 v75, v245, v83, s[20:21]
	v_cndmask_b32_e64 v74, v245, v82, s[20:21]
	v_cndmask_b32_e64 v73, v245, v81, s[20:21]
	v_cndmask_b32_e64 v72, v245, v80, s[20:21]
	s_and_b64 vcc, exec, s[18:19]
	global_store_dwordx4 v[108:109], v[68:71], off offset:512 sc0 sc1 nt
	global_store_dwordx4 v[110:111], v[72:75], off offset:512 sc0 sc1 nt
	s_cbranch_vccnz .LBB0_877
	v_readlane_b32 s22, v254, 56
	v_readlane_b32 s23, v254, 57
	s_add_i32 s22, s68, s22
	s_ashr_i32 s23, s22, 31
	v_pk_fma_f32 v[70:71], v[168:169], v[70:71], v[78:79]
	v_pk_fma_f32 v[68:69], v[166:167], v[68:69], v[76:77]
	v_pk_fma_f32 v[72:73], v[166:167], v[72:73], v[76:77]
	s_lshl_b64 s[22:23], s[22:23], 12
	v_cvt_pk_bf16_f32 v68, v68, v69
	v_cvt_pk_bf16_f32 v69, v70, v71
	v_cvt_pk_bf16_f32 v70, v72, v73
	v_lshl_add_u64 v[72:73], v[174:175], 0, s[22:23]
	v_pk_fma_f32 v[74:75], v[168:169], v[74:75], v[78:79]
	s_nop 0
	v_cvt_pk_bf16_f32 v71, v74, v75
	global_store_dwordx2 v[72:73], v[68:69], off offset:256
	v_add_co_u32_e32 v68, vcc, 0x8000, v72
	s_nop 1
	v_addc_co_u32_e32 v69, vcc, 0, v73, vcc
	global_store_dwordx2 v[68:69], v[70:71], off offset:256
.LBB0_877:
	ds_write_b128 v182, v[52:55]
	ds_write_b128 v182, v[56:59] offset:64
	ds_read_b128 v[56:59], v184
	ds_read_b128 v[52:55], v184 offset:1152
	s_waitcnt lgkmcnt(4)
	v_sub_f32_e32 v69, v85, v60
	v_sub_f32_e32 v68, v84, v60
	v_sub_f32_e32 v65, v65, v62
	v_sub_f32_e32 v64, v64, v62
	s_add_u32 s22, s6, s62
	v_sub_f32_e32 v71, v87, v60
	v_sub_f32_e32 v70, v86, v60
	v_pk_mul_f32 v[68:69], v[60:61], v[68:69] op_sel:[1,0]
	v_sub_f32_e32 v67, v67, v62
	v_sub_f32_e32 v66, v66, v62
	v_pk_mul_f32 v[64:65], v[62:63], v[64:65] op_sel:[1,0]
	s_addc_u32 s23, s7, s63
	v_pk_mul_f32 v[70:71], v[60:61], v[70:71] op_sel:[1,0]
	v_pk_fma_f32 v[68:69], v[104:105], v[68:69], v[112:113]
	v_pk_mul_f32 v[66:67], v[62:63], v[66:67] op_sel:[1,0]
	v_pk_fma_f32 v[72:73], v[104:105], v[64:65], v[112:113]
	v_pk_fma_f32 v[70:71], v[106:107], v[70:71], v[114:115]
	v_pk_fma_f32 v[74:75], v[106:107], v[66:67], v[114:115]
	v_cndmask_b32_e64 v65, v245, v69, s[20:21]
	v_cndmask_b32_e64 v64, v245, v68, s[20:21]
	v_cndmask_b32_e64 v69, v245, v73, s[20:21]
	v_cndmask_b32_e64 v68, v245, v72, s[20:21]
	v_lshl_add_u64 v[72:73], v[176:177], 2, s[22:23]
	v_cndmask_b32_e64 v66, v245, v70, s[20:21]
	v_cndmask_b32_e64 v70, v245, v74, s[20:21]
	v_add_co_u32_e32 v74, vcc, 0x10000, v72
	v_cndmask_b32_e64 v67, v245, v71, s[20:21]
	v_cndmask_b32_e64 v71, v245, v75, s[20:21]
	v_addc_co_u32_e32 v75, vcc, 0, v73, vcc
	s_and_b64 vcc, exec, s[18:19]
	global_store_dwordx4 v[72:73], v[64:67], off sc0 sc1 nt
	global_store_dwordx4 v[74:75], v[68:71], off sc0 sc1 nt
	s_cbranch_vccnz .LBB0_879
	s_add_i32 s22, s68, s58
	s_ashr_i32 s23, s22, 31
	v_pk_fma_f32 v[66:67], v[172:173], v[66:67], v[102:103]
	v_pk_fma_f32 v[64:65], v[170:171], v[64:65], v[100:101]
	v_pk_fma_f32 v[68:69], v[170:171], v[68:69], v[100:101]
	s_lshl_b64 s[22:23], s[22:23], 12
	v_cvt_pk_bf16_f32 v64, v64, v65
	v_cvt_pk_bf16_f32 v65, v66, v67
	v_cvt_pk_bf16_f32 v66, v68, v69
	v_lshl_add_u64 v[68:69], v[174:175], 0, s[22:23]
	v_pk_fma_f32 v[70:71], v[172:173], v[70:71], v[102:103]
	s_nop 0
	v_cvt_pk_bf16_f32 v67, v70, v71
	global_store_dwordx2 v[68:69], v[64:65], off
	v_add_co_u32_e32 v64, vcc, 0x8000, v68
	s_nop 1
	v_addc_co_u32_e32 v65, vcc, 0, v69, vcc
	global_store_dwordx2 v[64:65], v[66:67], off
.LBB0_879:
	ds_write_b128 v182, v[44:47]
	ds_write_b128 v182, v[48:51] offset:64
	ds_read_b128 v[64:67], v184
	ds_read_b128 v[48:51], v184 offset:1152
	ds_read2_b64 v[44:47], v187 offset0:144 offset1:152
	v_mov_b32_e32 v68, v61
	v_mov_b32_e32 v69, v61
	v_mov_b32_e32 v70, v63
	v_mov_b32_e32 v71, v63
	v_lshl_add_u64 v[74:75], v[72:73], 0, s[76:77]
	s_waitcnt lgkmcnt(6)
	v_sub_f32_e32 v57, v57, v60
	v_sub_f32_e32 v56, v56, v60
	v_sub_f32_e32 v59, v59, v60
	v_sub_f32_e32 v58, v58, v60
	v_mov_b32_e32 v60, v61
	s_waitcnt lgkmcnt(5)
	v_sub_f32_e32 v53, v53, v62
	v_sub_f32_e32 v52, v52, v62
	v_sub_f32_e32 v55, v55, v62
	v_sub_f32_e32 v54, v54, v62
	v_mov_b32_e32 v62, v63
	v_pk_mul_f32 v[58:59], v[60:61], v[58:59]
	v_pk_mul_f32 v[56:57], v[68:69], v[56:57]
	v_pk_mul_f32 v[54:55], v[62:63], v[54:55]
	v_pk_mul_f32 v[52:53], v[70:71], v[52:53]
	v_pk_fma_f32 v[56:57], v[88:89], v[56:57], v[92:93]
	v_pk_fma_f32 v[58:59], v[90:91], v[58:59], v[94:95]
	v_pk_fma_f32 v[60:61], v[88:89], v[52:53], v[92:93]
	v_pk_fma_f32 v[62:63], v[90:91], v[54:55], v[94:95]
	v_cndmask_b32_e64 v55, v245, v59, s[20:21]
	v_cndmask_b32_e64 v54, v245, v58, s[20:21]
	v_cndmask_b32_e64 v53, v245, v57, s[20:21]
	v_cndmask_b32_e64 v52, v245, v56, s[20:21]
	v_cndmask_b32_e64 v59, v245, v63, s[20:21]
	v_cndmask_b32_e64 v58, v245, v62, s[20:21]
	v_cndmask_b32_e64 v57, v245, v61, s[20:21]
	v_cndmask_b32_e64 v56, v245, v60, s[20:21]
	s_and_b64 vcc, exec, s[18:19]
	global_store_dwordx4 v[72:73], v[52:55], off offset:512 sc0 sc1 nt
	global_store_dwordx4 v[74:75], v[56:59], off offset:512 sc0 sc1 nt
	s_cbranch_vccnz .LBB0_881
	s_add_i32 s22, s68, s58
	s_ashr_i32 s23, s22, 31
	v_pk_fma_f32 v[54:55], v[168:169], v[54:55], v[78:79]
	v_pk_fma_f32 v[52:53], v[166:167], v[52:53], v[76:77]
	v_pk_fma_f32 v[56:57], v[166:167], v[56:57], v[76:77]
	s_lshl_b64 s[22:23], s[22:23], 12
	v_cvt_pk_bf16_f32 v52, v52, v53
	v_cvt_pk_bf16_f32 v53, v54, v55
	v_cvt_pk_bf16_f32 v54, v56, v57
	v_lshl_add_u64 v[56:57], v[174:175], 0, s[22:23]
	v_pk_fma_f32 v[58:59], v[168:169], v[58:59], v[78:79]
	s_nop 0
	v_cvt_pk_bf16_f32 v55, v58, v59
	global_store_dwordx2 v[56:57], v[52:53], off offset:256
	v_add_co_u32_e32 v52, vcc, 0x8000, v56
	s_nop 1
	v_addc_co_u32_e32 v53, vcc, 0, v57, vcc
	global_store_dwordx2 v[52:53], v[54:55], off offset:256
.LBB0_881:
	ds_write_b128 v182, v[36:39]
	ds_write_b128 v182, v[40:43] offset:64
	ds_read_b128 v[40:43], v184
	ds_read_b128 v[36:39], v184 offset:1152
	s_waitcnt lgkmcnt(4)
	v_sub_f32_e32 v53, v65, v44
	v_sub_f32_e32 v52, v64, v44
	v_sub_f32_e32 v49, v49, v46
	v_sub_f32_e32 v48, v48, v46
	s_add_u32 s22, s6, s96
	v_sub_f32_e32 v55, v67, v44
	v_sub_f32_e32 v54, v66, v44
	v_pk_mul_f32 v[52:53], v[44:45], v[52:53] op_sel:[1,0]
	v_sub_f32_e32 v51, v51, v46
	v_sub_f32_e32 v50, v50, v46
	v_pk_mul_f32 v[48:49], v[46:47], v[48:49] op_sel:[1,0]
	s_addc_u32 s23, s7, s97
	v_pk_mul_f32 v[54:55], v[44:45], v[54:55] op_sel:[1,0]
	v_pk_fma_f32 v[52:53], v[104:105], v[52:53], v[112:113]
	v_pk_mul_f32 v[50:51], v[46:47], v[50:51] op_sel:[1,0]
	v_pk_fma_f32 v[56:57], v[104:105], v[48:49], v[112:113]
	v_pk_fma_f32 v[54:55], v[106:107], v[54:55], v[114:115]
	v_pk_fma_f32 v[58:59], v[106:107], v[50:51], v[114:115]
	v_cndmask_b32_e64 v49, v245, v53, s[20:21]
	v_cndmask_b32_e64 v48, v245, v52, s[20:21]
	v_cndmask_b32_e64 v53, v245, v57, s[20:21]
	v_cndmask_b32_e64 v52, v245, v56, s[20:21]
	v_lshl_add_u64 v[56:57], v[176:177], 2, s[22:23]
	v_cndmask_b32_e64 v50, v245, v54, s[20:21]
	v_cndmask_b32_e64 v54, v245, v58, s[20:21]
	v_add_co_u32_e32 v58, vcc, 0x10000, v56
	v_cndmask_b32_e64 v51, v245, v55, s[20:21]
	v_cndmask_b32_e64 v55, v245, v59, s[20:21]
	v_addc_co_u32_e32 v59, vcc, 0, v57, vcc
	s_and_b64 vcc, exec, s[18:19]
	global_store_dwordx4 v[56:57], v[48:51], off sc0 sc1 nt
	global_store_dwordx4 v[58:59], v[52:55], off sc0 sc1 nt
	s_cbranch_vccnz .LBB0_883
	s_add_i32 s22, s68, s44
	s_ashr_i32 s23, s22, 31
	v_pk_fma_f32 v[50:51], v[172:173], v[50:51], v[102:103]
	v_pk_fma_f32 v[48:49], v[170:171], v[48:49], v[100:101]
	v_pk_fma_f32 v[52:53], v[170:171], v[52:53], v[100:101]
	s_lshl_b64 s[22:23], s[22:23], 12
	v_cvt_pk_bf16_f32 v48, v48, v49
	v_cvt_pk_bf16_f32 v49, v50, v51
	v_cvt_pk_bf16_f32 v50, v52, v53
	v_lshl_add_u64 v[52:53], v[174:175], 0, s[22:23]
	v_pk_fma_f32 v[54:55], v[172:173], v[54:55], v[102:103]
	s_nop 0
	v_cvt_pk_bf16_f32 v51, v54, v55
	global_store_dwordx2 v[52:53], v[48:49], off
	v_add_co_u32_e32 v48, vcc, 0x8000, v52
	s_nop 1
	v_addc_co_u32_e32 v49, vcc, 0, v53, vcc
	global_store_dwordx2 v[48:49], v[50:51], off
.LBB0_883:
	ds_write_b128 v182, v[28:31]
	ds_write_b128 v182, v[32:35] offset:64
	ds_read_b128 v[48:51], v184
	ds_read_b128 v[32:35], v184 offset:1152
	ds_read2_b64 v[28:31], v187 offset0:160 offset1:168
	v_mov_b32_e32 v52, v45
	v_mov_b32_e32 v53, v45
	v_mov_b32_e32 v54, v47
	v_mov_b32_e32 v55, v47
	v_lshl_add_u64 v[58:59], v[56:57], 0, s[76:77]
	s_waitcnt lgkmcnt(6)
	v_sub_f32_e32 v41, v41, v44
	v_sub_f32_e32 v40, v40, v44
	v_sub_f32_e32 v43, v43, v44
	v_sub_f32_e32 v42, v42, v44
	v_mov_b32_e32 v44, v45
	s_waitcnt lgkmcnt(5)
	v_sub_f32_e32 v37, v37, v46
	v_sub_f32_e32 v36, v36, v46
	v_sub_f32_e32 v39, v39, v46
	v_sub_f32_e32 v38, v38, v46
	v_mov_b32_e32 v46, v47
	v_pk_mul_f32 v[42:43], v[44:45], v[42:43]
	v_pk_mul_f32 v[40:41], v[52:53], v[40:41]
	v_pk_mul_f32 v[38:39], v[46:47], v[38:39]
	v_pk_mul_f32 v[36:37], v[54:55], v[36:37]
	v_pk_fma_f32 v[40:41], v[88:89], v[40:41], v[92:93]
	v_pk_fma_f32 v[42:43], v[90:91], v[42:43], v[94:95]
	v_pk_fma_f32 v[44:45], v[88:89], v[36:37], v[92:93]
	v_pk_fma_f32 v[46:47], v[90:91], v[38:39], v[94:95]
	v_cndmask_b32_e64 v39, v245, v43, s[20:21]
	v_cndmask_b32_e64 v38, v245, v42, s[20:21]
	v_cndmask_b32_e64 v37, v245, v41, s[20:21]
	v_cndmask_b32_e64 v36, v245, v40, s[20:21]
	v_cndmask_b32_e64 v43, v245, v47, s[20:21]
	v_cndmask_b32_e64 v42, v245, v46, s[20:21]
	v_cndmask_b32_e64 v41, v245, v45, s[20:21]
	v_cndmask_b32_e64 v40, v245, v44, s[20:21]
	s_and_b64 vcc, exec, s[18:19]
	global_store_dwordx4 v[56:57], v[36:39], off offset:512 sc0 sc1 nt
	global_store_dwordx4 v[58:59], v[40:43], off offset:512 sc0 sc1 nt
	s_cbranch_vccnz .LBB0_885
	s_add_i32 s22, s68, s44
	s_ashr_i32 s23, s22, 31
	v_pk_fma_f32 v[38:39], v[168:169], v[38:39], v[78:79]
	v_pk_fma_f32 v[36:37], v[166:167], v[36:37], v[76:77]
	v_pk_fma_f32 v[40:41], v[166:167], v[40:41], v[76:77]
	s_lshl_b64 s[22:23], s[22:23], 12
	v_cvt_pk_bf16_f32 v36, v36, v37
	v_cvt_pk_bf16_f32 v37, v38, v39
	v_cvt_pk_bf16_f32 v38, v40, v41
	v_lshl_add_u64 v[40:41], v[174:175], 0, s[22:23]
	v_pk_fma_f32 v[42:43], v[168:169], v[42:43], v[78:79]
	s_nop 0
	v_cvt_pk_bf16_f32 v39, v42, v43
	global_store_dwordx2 v[40:41], v[36:37], off offset:256
	v_add_co_u32_e32 v36, vcc, 0x8000, v40
	s_nop 1
	v_addc_co_u32_e32 v37, vcc, 0, v41, vcc
	global_store_dwordx2 v[36:37], v[38:39], off offset:256
.LBB0_885:
	ds_write_b128 v182, v[20:23]
	ds_write_b128 v182, v[24:27] offset:64
	ds_read_b128 v[24:27], v184
	ds_read_b128 v[20:23], v184 offset:1152
	s_waitcnt lgkmcnt(4)
	v_sub_f32_e32 v37, v49, v28
	v_sub_f32_e32 v36, v48, v28
	v_sub_f32_e32 v33, v33, v30
	v_sub_f32_e32 v32, v32, v30
	s_add_u32 s22, s6, s70
	v_sub_f32_e32 v39, v51, v28
	v_sub_f32_e32 v38, v50, v28
	v_pk_mul_f32 v[36:37], v[28:29], v[36:37] op_sel:[1,0]
	v_sub_f32_e32 v35, v35, v30
	v_sub_f32_e32 v34, v34, v30
	v_pk_mul_f32 v[32:33], v[30:31], v[32:33] op_sel:[1,0]
	s_addc_u32 s23, s7, s71
	v_pk_mul_f32 v[38:39], v[28:29], v[38:39] op_sel:[1,0]
	v_pk_fma_f32 v[36:37], v[104:105], v[36:37], v[112:113]
	v_pk_mul_f32 v[34:35], v[30:31], v[34:35] op_sel:[1,0]
	v_pk_fma_f32 v[40:41], v[104:105], v[32:33], v[112:113]
	v_pk_fma_f32 v[38:39], v[106:107], v[38:39], v[114:115]
	v_pk_fma_f32 v[42:43], v[106:107], v[34:35], v[114:115]
	v_cndmask_b32_e64 v33, v245, v37, s[20:21]
	v_cndmask_b32_e64 v32, v245, v36, s[20:21]
	v_cndmask_b32_e64 v37, v245, v41, s[20:21]
	v_cndmask_b32_e64 v36, v245, v40, s[20:21]
	v_lshl_add_u64 v[40:41], v[176:177], 2, s[22:23]
	v_cndmask_b32_e64 v34, v245, v38, s[20:21]
	v_cndmask_b32_e64 v38, v245, v42, s[20:21]
	v_add_co_u32_e32 v42, vcc, 0x10000, v40
	v_cndmask_b32_e64 v35, v245, v39, s[20:21]
	v_cndmask_b32_e64 v39, v245, v43, s[20:21]
	v_addc_co_u32_e32 v43, vcc, 0, v41, vcc
	s_and_b64 vcc, exec, s[18:19]
	global_store_dwordx4 v[40:41], v[32:35], off sc0 sc1 nt
	global_store_dwordx4 v[42:43], v[36:39], off sc0 sc1 nt
	s_cbranch_vccnz .LBB0_887
	s_add_i32 s22, s68, s2
	s_ashr_i32 s23, s22, 31
	v_pk_fma_f32 v[34:35], v[172:173], v[34:35], v[102:103]
	v_pk_fma_f32 v[32:33], v[170:171], v[32:33], v[100:101]
	v_pk_fma_f32 v[36:37], v[170:171], v[36:37], v[100:101]
	s_lshl_b64 s[22:23], s[22:23], 12
	v_cvt_pk_bf16_f32 v32, v32, v33
	v_cvt_pk_bf16_f32 v33, v34, v35
	v_cvt_pk_bf16_f32 v34, v36, v37
	v_lshl_add_u64 v[36:37], v[174:175], 0, s[22:23]
	v_pk_fma_f32 v[38:39], v[172:173], v[38:39], v[102:103]
	s_nop 0
	v_cvt_pk_bf16_f32 v35, v38, v39
	global_store_dwordx2 v[36:37], v[32:33], off
	v_add_co_u32_e32 v32, vcc, 0x8000, v36
	s_nop 1
	v_addc_co_u32_e32 v33, vcc, 0, v37, vcc
	global_store_dwordx2 v[32:33], v[34:35], off
.LBB0_887:
	ds_write_b128 v182, v[12:15]
	ds_write_b128 v182, v[16:19] offset:64
	ds_read_b128 v[32:35], v184
	ds_read_b128 v[16:19], v184 offset:1152
	ds_read2_b64 v[12:15], v187 offset0:176 offset1:184
	v_mov_b32_e32 v36, v29
	v_mov_b32_e32 v37, v29
	v_mov_b32_e32 v38, v31
	v_mov_b32_e32 v39, v31
	v_lshl_add_u64 v[42:43], v[40:41], 0, s[76:77]
	s_waitcnt lgkmcnt(6)
	v_sub_f32_e32 v25, v25, v28
	v_sub_f32_e32 v24, v24, v28
	v_sub_f32_e32 v27, v27, v28
	v_sub_f32_e32 v26, v26, v28
	v_mov_b32_e32 v28, v29
	s_waitcnt lgkmcnt(5)
	v_sub_f32_e32 v21, v21, v30
	v_sub_f32_e32 v20, v20, v30
	v_sub_f32_e32 v23, v23, v30
	v_sub_f32_e32 v22, v22, v30
	v_mov_b32_e32 v30, v31
	v_pk_mul_f32 v[26:27], v[28:29], v[26:27]
	v_pk_mul_f32 v[24:25], v[36:37], v[24:25]
	v_pk_mul_f32 v[22:23], v[30:31], v[22:23]
	v_pk_mul_f32 v[20:21], v[38:39], v[20:21]
	v_pk_fma_f32 v[24:25], v[88:89], v[24:25], v[92:93]
	v_pk_fma_f32 v[26:27], v[90:91], v[26:27], v[94:95]
	v_pk_fma_f32 v[28:29], v[88:89], v[20:21], v[92:93]
	v_pk_fma_f32 v[30:31], v[90:91], v[22:23], v[94:95]
	v_cndmask_b32_e64 v23, v245, v27, s[20:21]
	v_cndmask_b32_e64 v22, v245, v26, s[20:21]
	v_cndmask_b32_e64 v21, v245, v25, s[20:21]
	v_cndmask_b32_e64 v20, v245, v24, s[20:21]
	v_cndmask_b32_e64 v27, v245, v31, s[20:21]
	v_cndmask_b32_e64 v26, v245, v30, s[20:21]
	v_cndmask_b32_e64 v25, v245, v29, s[20:21]
	v_cndmask_b32_e64 v24, v245, v28, s[20:21]
	s_and_b64 vcc, exec, s[18:19]
	global_store_dwordx4 v[40:41], v[20:23], off offset:512 sc0 sc1 nt
	global_store_dwordx4 v[42:43], v[24:27], off offset:512 sc0 sc1 nt
	s_cbranch_vccnz .LBB0_889
	s_add_i32 s22, s68, s2
	s_ashr_i32 s23, s22, 31
	v_pk_fma_f32 v[22:23], v[168:169], v[22:23], v[78:79]
	v_pk_fma_f32 v[20:21], v[166:167], v[20:21], v[76:77]
	v_pk_fma_f32 v[24:25], v[166:167], v[24:25], v[76:77]
	s_lshl_b64 s[22:23], s[22:23], 12
	v_cvt_pk_bf16_f32 v20, v20, v21
	v_cvt_pk_bf16_f32 v21, v22, v23
	v_cvt_pk_bf16_f32 v22, v24, v25
	v_lshl_add_u64 v[24:25], v[174:175], 0, s[22:23]
	v_pk_fma_f32 v[26:27], v[168:169], v[26:27], v[78:79]
	s_nop 0
	v_cvt_pk_bf16_f32 v23, v26, v27
	global_store_dwordx2 v[24:25], v[20:21], off offset:256
	v_add_co_u32_e32 v20, vcc, 0x8000, v24
	s_nop 1
	v_addc_co_u32_e32 v21, vcc, 0, v25, vcc
	global_store_dwordx2 v[20:21], v[22:23], off offset:256
.LBB0_889:
	ds_write_b128 v182, v[4:7]
	ds_write_b128 v182, v[8:11] offset:64
	ds_read_b128 v[8:11], v184
	ds_read_b128 v[4:7], v184 offset:1152
	s_waitcnt lgkmcnt(4)
	v_sub_f32_e32 v21, v33, v12
	v_sub_f32_e32 v20, v32, v12
	v_sub_f32_e32 v17, v17, v14
	v_sub_f32_e32 v16, v16, v14
	s_add_u32 s6, s6, s14
	v_sub_f32_e32 v23, v35, v12
	v_sub_f32_e32 v22, v34, v12
	v_pk_mul_f32 v[20:21], v[12:13], v[20:21] op_sel:[1,0]
	v_sub_f32_e32 v19, v19, v14
	v_sub_f32_e32 v18, v18, v14
	v_pk_mul_f32 v[16:17], v[14:15], v[16:17] op_sel:[1,0]
	s_addc_u32 s7, s7, s15
	v_pk_mul_f32 v[22:23], v[12:13], v[22:23] op_sel:[1,0]
	v_pk_fma_f32 v[20:21], v[104:105], v[20:21], v[112:113]
	v_pk_mul_f32 v[18:19], v[14:15], v[18:19] op_sel:[1,0]
	v_pk_fma_f32 v[24:25], v[104:105], v[16:17], v[112:113]
	v_pk_fma_f32 v[22:23], v[106:107], v[22:23], v[114:115]
	v_pk_fma_f32 v[26:27], v[106:107], v[18:19], v[114:115]
	v_cndmask_b32_e64 v17, v245, v21, s[20:21]
	v_cndmask_b32_e64 v16, v245, v20, s[20:21]
	v_cndmask_b32_e64 v21, v245, v25, s[20:21]
	v_cndmask_b32_e64 v20, v245, v24, s[20:21]
	v_lshl_add_u64 v[24:25], v[176:177], 2, s[6:7]
	v_cndmask_b32_e64 v18, v245, v22, s[20:21]
	v_cndmask_b32_e64 v22, v245, v26, s[20:21]
	v_add_co_u32_e32 v26, vcc, 0x10000, v24
	v_cndmask_b32_e64 v19, v245, v23, s[20:21]
	v_cndmask_b32_e64 v23, v245, v27, s[20:21]
	v_addc_co_u32_e32 v27, vcc, 0, v25, vcc
	s_and_b64 vcc, exec, s[18:19]
	global_store_dwordx4 v[24:25], v[16:19], off sc0 sc1 nt
	global_store_dwordx4 v[26:27], v[20:23], off sc0 sc1 nt
	s_cbranch_vccnz .LBB0_891
	s_add_i32 s6, s68, s4
	s_ashr_i32 s7, s6, 31
	v_pk_fma_f32 v[18:19], v[172:173], v[18:19], v[102:103]
	v_pk_fma_f32 v[16:17], v[170:171], v[16:17], v[100:101]
	v_pk_fma_f32 v[20:21], v[170:171], v[20:21], v[100:101]
	s_lshl_b64 s[6:7], s[6:7], 12
	v_cvt_pk_bf16_f32 v16, v16, v17
	v_cvt_pk_bf16_f32 v17, v18, v19
	v_cvt_pk_bf16_f32 v18, v20, v21
	v_lshl_add_u64 v[20:21], v[174:175], 0, s[6:7]
	v_pk_fma_f32 v[22:23], v[172:173], v[22:23], v[102:103]
	s_nop 0
	v_cvt_pk_bf16_f32 v19, v22, v23
	global_store_dwordx2 v[20:21], v[16:17], off
	v_add_co_u32_e32 v16, vcc, 0x8000, v20
	s_nop 1
	v_addc_co_u32_e32 v17, vcc, 0, v21, vcc
	global_store_dwordx2 v[16:17], v[18:19], off
.LBB0_891:
	v_mov_b32_e32 v16, v13
	v_mov_b32_e32 v17, v13
	v_mov_b32_e32 v18, v15
	v_mov_b32_e32 v19, v15
	v_lshl_add_u64 v[20:21], v[24:25], 0, s[76:77]
	s_waitcnt lgkmcnt(1)
	v_sub_f32_e32 v9, v9, v12
	v_sub_f32_e32 v8, v8, v12
	v_sub_f32_e32 v11, v11, v12
	v_sub_f32_e32 v10, v10, v12
	v_mov_b32_e32 v12, v13
	s_waitcnt lgkmcnt(0)
	v_sub_f32_e32 v5, v5, v14
	v_sub_f32_e32 v4, v4, v14
	v_sub_f32_e32 v7, v7, v14
	v_sub_f32_e32 v6, v6, v14
	v_mov_b32_e32 v14, v15
	v_pk_mul_f32 v[10:11], v[12:13], v[10:11]
	v_pk_mul_f32 v[8:9], v[16:17], v[8:9]
	v_pk_mul_f32 v[6:7], v[14:15], v[6:7]
	v_pk_mul_f32 v[4:5], v[18:19], v[4:5]
	v_pk_fma_f32 v[8:9], v[88:89], v[8:9], v[92:93]
	v_pk_fma_f32 v[10:11], v[90:91], v[10:11], v[94:95]
	v_pk_fma_f32 v[12:13], v[88:89], v[4:5], v[92:93]
	v_pk_fma_f32 v[14:15], v[90:91], v[6:7], v[94:95]
	v_cndmask_b32_e64 v7, v245, v11, s[20:21]
	v_cndmask_b32_e64 v6, v245, v10, s[20:21]
	v_cndmask_b32_e64 v5, v245, v9, s[20:21]
	v_cndmask_b32_e64 v4, v245, v8, s[20:21]
	v_cndmask_b32_e64 v11, v245, v15, s[20:21]
	v_cndmask_b32_e64 v10, v245, v14, s[20:21]
	v_cndmask_b32_e64 v9, v245, v13, s[20:21]
	v_cndmask_b32_e64 v8, v245, v12, s[20:21]
	s_and_b64 vcc, exec, s[18:19]
	global_store_dwordx4 v[24:25], v[4:7], off offset:512 sc0 sc1 nt
	global_store_dwordx4 v[20:21], v[8:11], off offset:512 sc0 sc1 nt
	s_cbranch_vccnz .LBB0_893
	s_add_i32 s6, s68, s4
	s_ashr_i32 s7, s6, 31
	v_pk_fma_f32 v[6:7], v[168:169], v[6:7], v[78:79]
	v_pk_fma_f32 v[4:5], v[166:167], v[4:5], v[76:77]
	v_pk_fma_f32 v[8:9], v[166:167], v[8:9], v[76:77]
	s_lshl_b64 s[6:7], s[6:7], 12
	v_cvt_pk_bf16_f32 v4, v4, v5
	v_cvt_pk_bf16_f32 v5, v6, v7
	v_cvt_pk_bf16_f32 v6, v8, v9
	v_lshl_add_u64 v[8:9], v[174:175], 0, s[6:7]
	v_pk_fma_f32 v[10:11], v[168:169], v[10:11], v[78:79]
	s_nop 0
	v_cvt_pk_bf16_f32 v7, v10, v11
	global_store_dwordx2 v[8:9], v[4:5], off offset:256
	v_add_co_u32_e32 v4, vcc, 0x8000, v8
	s_nop 1
	v_addc_co_u32_e32 v5, vcc, 0, v9, vcc
	global_store_dwordx2 v[4:5], v[6:7], off offset:256
